# weight-transpose items: 16 LDS read-backs hoisted and waited with counted lgkmcnt (16 regions) on top of previous best
# speedup vs baseline: 1.0083x; 1.0083x over previous
; __device__ __forceinline__ unsigned cvt_pk_bf16(float lo, float hi) { unsigned r; asm volatile("v_cvt_pk_bf16_f32 %0, %1, %2" : "=v"(r) : "v"(lo), "v"(hi)); return r; }
; #define LAS __attribute__((address_space(3)))
; __device__ __forceinline__ void transpose_item(const float* W, int K, int N, bf16_t* WT, const float* kscale, int kind, LAS float* scr, int item, int lane) {
;     const int nblk = N / 32, kb = item / nblk, nb = item % nblk, k0 = 64 * kb, n0 = 32 * nb;
;     {
;         const float* src = W + (size_t)(k0 + (lane >> 3)) * N + n0 + (lane & 7) * 4;
;         f32x4 t[8];
; #pragma unroll
;         for (int i = 0; i < 8; ++i) t[i] = *(const f32x4*)(src + (size_t)(8 * i) * N);
; #pragma unroll
;         for (int i = 0; i < 8; ++i) {
;             const int kk = 8 * i + (lane >> 3);
;             f32x4 v = t[i]; if (kscale) v = v * kscale[k0 + kk];
;             LAS float* d = scr + kk * 33 + (lane & 7) * 4;
;             d[0] = v[0]; d[1] = v[1]; d[2] = v[2]; d[3] = v[3];
;         }
;     }
;     asm volatile("s_waitcnt lgkmcnt(0)" ::: "memory");
;     const int c = lane & 7;
; #pragma unroll
;     for (int j = 0; j < 4; ++j) {
;         const int n = (lane >> 3) + 8 * j; const LAS float* s = scr + (8 * c) * 33 + n;
;         int drow; float sc; map_col(kind, n0 + n, drow, sc);
;         u32x4 ov; ov.x = cvt_pk_bf16(s[0 * 33] * sc, s[1 * 33] * sc); ov.y = cvt_pk_bf16(s[2 * 33] * sc, s[3 * 33] * sc); ov.z = cvt_pk_bf16(s[4 * 33] * sc, s[5 * 33] * sc); ov.w = cvt_pk_bf16(s[6 * 33] * sc, s[7 * 33] * sc);
;         *(u32x4*)(WT + (size_t)drow * K + k0 + 8 * c) = ov;
;     }
;     asm volatile("s_waitcnt lgkmcnt(0)" ::: "memory");
;     ...
;             transpose_matrix(p.in[I_SBW_OUT], DM, DM, (bf16_t*)(wsw + W0_OUT), nullptr, MAP_ID, scr, gw, NGW, lane);
.LBB0_93:
	s_ashr_i32 s24, s23, 31
	s_lshr_b32 s24, s24, 26
	s_add_i32 s25, s23, s24
	s_and_b32 s24, s25, 0xffffffc0
	s_lshl_b32 s25, s25, 5
	v_or_b32_e32 v24, s24, v1
	s_and_b32 s25, s25, 0xfffff800
	v_ashrrev_i32_e32 v25, 31, v24
	s_sub_i32 s26, s6, s25
	v_lshlrev_b64 v[24:25], 13, v[24:25]
	s_ashr_i32 s27, s26, 31
	v_lshl_add_u64 v[24:25], s[4:5], 0, v[24:25]
	v_lshl_add_u64 v[24:25], s[26:27], 2, v[24:25]
	v_lshl_add_u64 v[28:29], v[24:25], 0, v[2:3]
	v_add_co_u32_e32 v60, vcc, s8, v28
	global_load_dwordx4 v[24:27], v[28:29], off
	s_nop 0
	v_addc_co_u32_e32 v61, vcc, 0, v29, vcc
	v_add_co_u32_e32 v62, vcc, s9, v28
	s_ashr_i32 s25, s24, 31
	s_nop 0
	v_addc_co_u32_e32 v63, vcc, 0, v29, vcc
	v_add_co_u32_e32 v64, vcc, s18, v28
	s_add_i32 s23, s23, s10
	s_nop 0
	v_addc_co_u32_e32 v65, vcc, 0, v29, vcc
	v_add_co_u32_e32 v66, vcc, s19, v28
	s_add_i32 s6, s6, s7
	s_nop 0
	v_addc_co_u32_e32 v67, vcc, 0, v29, vcc
	v_add_co_u32_e32 v68, vcc, s20, v28
	s_cmpk_lt_i32 s23, 0x800
	s_nop 0
	v_addc_co_u32_e32 v69, vcc, 0, v29, vcc
	v_add_co_u32_e32 v70, vcc, s21, v28
	s_nop 1
	v_addc_co_u32_e32 v71, vcc, 0, v29, vcc
	v_add_co_u32_e32 v28, vcc, s22, v28
	s_nop 1
	v_addc_co_u32_e32 v29, vcc, 0, v29, vcc
	global_load_dwordx4 v[32:35], v[60:61], off
	global_load_dwordx4 v[36:39], v[62:63], off
	global_load_dwordx4 v[40:43], v[64:65], off
	global_load_dwordx4 v[44:47], v[66:67], off
	global_load_dwordx4 v[48:51], v[68:69], off
	global_load_dwordx4 v[52:55], v[70:71], off
	global_load_dwordx4 v[56:59], v[28:29], off
	v_add_u32_e32 v60, s26, v1
	v_ashrrev_i32_e32 v61, 31, v60
	v_lshl_add_u64 v[28:29], s[24:25], 1, v[4:5]
	v_lshlrev_b64 v[66:67], 12, v[60:61]
	v_add_u32_e32 v62, 8, v60
	v_lshl_add_u64 v[66:67], v[28:29], 0, v[66:67]
	v_ashrrev_i32_e32 v63, 31, v62
	v_lshlrev_b64 v[62:63], 12, v[62:63]
	v_add_u32_e32 v64, 16, v60
	v_lshl_add_u64 v[62:63], v[28:29], 0, v[62:63]
	v_ashrrev_i32_e32 v65, 31, v64
	v_lshlrev_b64 v[64:65], 12, v[64:65]
	v_lshl_add_u64 v[64:65], v[28:29], 0, v[64:65]
	s_waitcnt vmcnt(7)
	ds_write2_b32 v7, v24, v25 offset1:1
	ds_write2_b32 v7, v26, v27 offset0:2 offset1:3
	s_waitcnt vmcnt(6)
	ds_write2_b32 v8, v32, v33 offset1:1
	ds_write2_b32 v9, v34, v35 offset1:1
	s_waitcnt vmcnt(5)
	ds_write2_b32 v10, v36, v37 offset1:1
	ds_write2_b32 v11, v38, v39 offset1:1
	s_waitcnt vmcnt(4)
	ds_write2_b32 v12, v40, v41 offset1:1
	ds_write2_b32 v13, v42, v43 offset1:1
	s_waitcnt vmcnt(3)
	ds_write2_b32 v15, v44, v45 offset1:1
	ds_write2_b32 v16, v46, v47 offset1:1
	s_waitcnt vmcnt(2)
	ds_write2_b32 v17, v48, v49 offset1:1
	ds_write2_b32 v18, v50, v51 offset1:1
	s_waitcnt vmcnt(1)
	ds_write2_b32 v19, v52, v53 offset1:1
	ds_write2_b32 v20, v54, v55 offset1:1
	s_waitcnt vmcnt(0)
	ds_write2_b32 v21, v56, v57 offset1:1
	ds_write2_b32 v22, v58, v59 offset1:1
	s_waitcnt lgkmcnt(0)
	ds_read2_b32 v[100:101], v6 offset1:33
	ds_read2_b32 v[102:103], v6 offset0:66 offset1:99
	ds_read2_b32 v[104:105], v6 offset0:132 offset1:165
	ds_read2_b32 v[106:107], v6 offset0:198 offset1:231
	ds_read2_b32 v[108:109], v6 offset0:8 offset1:41
	ds_read2_b32 v[110:111], v6 offset0:74 offset1:107
	ds_read2_b32 v[112:113], v6 offset0:140 offset1:173
	ds_read2_b32 v[114:115], v6 offset0:206 offset1:239
	ds_read2_b32 v[116:117], v6 offset0:16 offset1:49
	ds_read2_b32 v[118:119], v6 offset0:82 offset1:115
	ds_read2_b32 v[120:121], v6 offset0:148 offset1:181
	ds_read2_b32 v[122:123], v6 offset0:214 offset1:247
	ds_read2_b32 v[124:125], v6 offset0:24 offset1:57
	ds_read2_b32 v[126:127], v6 offset0:90 offset1:123
	ds_read2_b32 v[128:129], v6 offset0:156 offset1:189
	ds_read2_b32 v[130:131], v6 offset0:222 offset1:255
	s_waitcnt lgkmcnt(15)
	v_cvt_pk_bf16_f32 v24, v100, v101
	s_waitcnt lgkmcnt(14)
	v_cvt_pk_bf16_f32 v25, v102, v103
	s_waitcnt lgkmcnt(13)
	v_cvt_pk_bf16_f32 v26, v104, v105
	s_waitcnt lgkmcnt(12)
	v_cvt_pk_bf16_f32 v27, v106, v107
	global_store_dwordx4 v[66:67], v[24:27], off
	v_add_u32_e32 v34, 24, v60
	v_ashrrev_i32_e32 v35, 31, v34
	s_waitcnt lgkmcnt(11)
	v_cvt_pk_bf16_f32 v24, v108, v109
	s_waitcnt lgkmcnt(10)
	v_cvt_pk_bf16_f32 v25, v110, v111
	s_waitcnt lgkmcnt(9)
	v_cvt_pk_bf16_f32 v26, v112, v113
	s_waitcnt lgkmcnt(8)
	v_cvt_pk_bf16_f32 v27, v114, v115
	global_store_dwordx4 v[62:63], v[24:27], off
	v_lshlrev_b64 v[34:35], 12, v[34:35]
	v_lshl_add_u64 v[28:29], v[28:29], 0, v[34:35]
	s_waitcnt lgkmcnt(7)
	v_cvt_pk_bf16_f32 v24, v116, v117
	s_waitcnt lgkmcnt(6)
	v_cvt_pk_bf16_f32 v25, v118, v119
	s_waitcnt lgkmcnt(5)
	v_cvt_pk_bf16_f32 v26, v120, v121
	s_waitcnt lgkmcnt(4)
	v_cvt_pk_bf16_f32 v27, v122, v123
	global_store_dwordx4 v[64:65], v[24:27], off
	s_nop 0
	s_waitcnt lgkmcnt(3)
	v_cvt_pk_bf16_f32 v24, v124, v125
	s_waitcnt lgkmcnt(2)
	v_cvt_pk_bf16_f32 v25, v126, v127
	s_waitcnt lgkmcnt(1)
	v_cvt_pk_bf16_f32 v26, v128, v129
	s_waitcnt lgkmcnt(0)
	v_cvt_pk_bf16_f32 v27, v130, v131
	global_store_dwordx4 v[28:29], v[24:27], off
	s_waitcnt lgkmcnt(0)
	s_cbranch_scc1 .LBB0_93

; __device__ __forceinline__ unsigned cvt_pk_bf16(float lo, float hi) { unsigned r; asm volatile("v_cvt_pk_bf16_f32 %0, %1, %2" : "=v"(r) : "v"(lo), "v"(hi)); return r; }
; #define LAS __attribute__((address_space(3)))
; __device__ __forceinline__ void transpose_item(const float* W, int K, int N, bf16_t* WT, const float* kscale, int kind, LAS float* scr, int item, int lane) {
;     const int nblk = N / 32, kb = item / nblk, nb = item % nblk, k0 = 64 * kb, n0 = 32 * nb;
;     {
;         const float* src = W + (size_t)(k0 + (lane >> 3)) * N + n0 + (lane & 7) * 4;
;         f32x4 t[8];
; #pragma unroll
;         for (int i = 0; i < 8; ++i) t[i] = *(const f32x4*)(src + (size_t)(8 * i) * N);
; #pragma unroll
;         for (int i = 0; i < 8; ++i) {
;             const int kk = 8 * i + (lane >> 3);
;             f32x4 v = t[i]; if (kscale) v = v * kscale[k0 + kk];
;             LAS float* d = scr + kk * 33 + (lane & 7) * 4;
;             d[0] = v[0]; d[1] = v[1]; d[2] = v[2]; d[3] = v[3];
;         }
;     }
;     asm volatile("s_waitcnt lgkmcnt(0)" ::: "memory");
;     const int c = lane & 7;
; #pragma unroll
;     for (int j = 0; j < 4; ++j) {
;         const int n = (lane >> 3) + 8 * j; const LAS float* s = scr + (8 * c) * 33 + n;
;         int drow; float sc; map_col(kind, n0 + n, drow, sc);
;         u32x4 ov; ov.x = cvt_pk_bf16(s[0 * 33] * sc, s[1 * 33] * sc); ov.y = cvt_pk_bf16(s[2 * 33] * sc, s[3 * 33] * sc); ov.z = cvt_pk_bf16(s[4 * 33] * sc, s[5 * 33] * sc); ov.w = cvt_pk_bf16(s[6 * 33] * sc, s[7 * 33] * sc);
;         *(u32x4*)(WT + (size_t)drow * K + k0 + 8 * c) = ov;
;     }
;     asm volatile("s_waitcnt lgkmcnt(0)" ::: "memory");
;     ...
;             transpose_matrix(p.in[I_WG], DM, FFN, (bf16_t*)(wsw + W0_GU), nullptr, MAP_GATE, scr, gw, NGW, lane);
.LBB0_96:
	s_mul_hi_i32 s26, s25, 0x2e8ba2e9
	s_lshr_b32 s27, s26, 31
	s_ashr_i32 s26, s26, 5
	s_add_i32 s27, s26, s27
	s_lshl_b32 s26, s27, 6
	s_mul_i32 s38, s27, 0xffffea00
	s_add_i32 s38, s24, s38
	v_or_b32_e32 v27, s26, v1
	v_mad_i64_i32 v[28:29], s[40:41], v27, s5, v[8:9]
	s_ashr_i32 s39, s38, 31
	v_lshl_add_u64 v[28:29], s[38:39], 2, v[28:29]
	v_lshl_add_u64 v[28:29], v[28:29], 0, v[2:3]
	v_add_co_u32_e32 v64, vcc, s8, v28
	global_load_dwordx4 v[32:35], v[28:29], off
	s_nop 0
	v_addc_co_u32_e32 v65, vcc, 0, v29, vcc
	v_add_co_u32_e32 v66, vcc, s9, v28
	s_mul_i32 s39, s27, 0xffffd400
	s_nop 0
	v_addc_co_u32_e32 v67, vcc, 0, v29, vcc
	v_add_co_u32_e32 v68, vcc, s18, v28
	v_add_u32_e32 v30, s38, v1
	s_nop 0
	v_addc_co_u32_e32 v69, vcc, 0, v29, vcc
	v_add_co_u32_e32 v70, vcc, s19, v28
	v_add_u32_e32 v27, s39, v26
	s_nop 0
	v_addc_co_u32_e32 v71, vcc, 0, v29, vcc
	v_add_co_u32_e32 v72, vcc, s20, v28
	s_ashr_i32 s27, s26, 31
	s_nop 0
	v_addc_co_u32_e32 v73, vcc, 0, v29, vcc
	v_add_co_u32_e32 v74, vcc, s21, v28
	s_add_i32 s25, s25, s10
	s_nop 0
	v_addc_co_u32_e32 v75, vcc, 0, v29, vcc
	v_add_co_u32_e32 v28, vcc, s22, v28
	s_add_i32 s24, s24, s7
	s_nop 0
	v_addc_co_u32_e32 v29, vcc, 0, v29, vcc
	global_load_dwordx4 v[36:39], v[64:65], off
	global_load_dwordx4 v[40:43], v[66:67], off
	global_load_dwordx4 v[44:47], v[68:69], off
	global_load_dwordx4 v[48:51], v[70:71], off
	global_load_dwordx4 v[52:55], v[72:73], off
	global_load_dwordx4 v[56:59], v[74:75], off
	global_load_dwordx4 v[60:63], v[28:29], off
	v_and_b32_e32 v64, 0x7f, v30
	v_add_u32_e32 v65, 8, v30
	v_and_or_b32 v64, v27, s23, v64
	v_and_b32_e32 v69, 0x7f, v65
	v_ashrrev_i32_e32 v65, 31, v64
	v_lshl_add_u64 v[28:29], s[26:27], 1, v[6:7]
	v_add_u32_e32 v66, 16, v27
	v_add_u32_e32 v68, 16, v30
	v_lshlrev_b64 v[64:65], 12, v[64:65]
	v_add_u32_e32 v67, 32, v27
	v_and_b32_e32 v68, 0x7f, v68
	v_and_or_b32 v66, v66, s23, v69
	v_lshl_add_u64 v[64:65], v[28:29], 0, v[64:65]
	v_and_or_b32 v68, v67, s23, v68
	v_ashrrev_i32_e32 v67, 31, v66
	v_lshlrev_b64 v[66:67], 12, v[66:67]
	v_lshl_add_u64 v[66:67], v[28:29], 0, v[66:67]
	v_add_u32_e32 v30, 24, v30
	v_ashrrev_i32_e32 v69, 31, v68
	v_add_u32_e32 v27, 48, v27
	v_and_b32_e32 v30, 0x7f, v30
	v_lshlrev_b64 v[68:69], 12, v[68:69]
	v_lshl_add_u64 v[68:69], v[28:29], 0, v[68:69]
	s_cmpk_lt_i32 s25, 0x1600
	v_add_u32_e32 v26, s4, v26
	s_waitcnt vmcnt(7)
	ds_write2_b32 v11, v32, v33 offset1:1
	ds_write2_b32 v11, v34, v35 offset0:2 offset1:3
	s_waitcnt vmcnt(6)
	ds_write2_b32 v12, v36, v37 offset1:1
	ds_write2_b32 v13, v38, v39 offset1:1
	s_waitcnt vmcnt(5)
	ds_write2_b32 v14, v40, v41 offset1:1
	ds_write2_b32 v15, v42, v43 offset1:1
	s_waitcnt vmcnt(4)
	ds_write2_b32 v16, v44, v45 offset1:1
	ds_write2_b32 v17, v46, v47 offset1:1
	s_waitcnt vmcnt(3)
	ds_write2_b32 v18, v48, v49 offset1:1
	ds_write2_b32 v19, v50, v51 offset1:1
	s_waitcnt vmcnt(2)
	ds_write2_b32 v20, v52, v53 offset1:1
	ds_write2_b32 v21, v54, v55 offset1:1
	s_waitcnt vmcnt(1)
	ds_write2_b32 v22, v56, v57 offset1:1
	ds_write2_b32 v23, v58, v59 offset1:1
	s_waitcnt vmcnt(0)
	ds_write2_b32 v24, v60, v61 offset1:1
	ds_write2_b32 v25, v62, v63 offset1:1
	s_waitcnt lgkmcnt(0)
	ds_read2_b32 v[100:101], v10 offset1:33
	ds_read2_b32 v[102:103], v10 offset0:66 offset1:99
	ds_read2_b32 v[104:105], v10 offset0:132 offset1:165
	ds_read2_b32 v[106:107], v10 offset0:198 offset1:231
	ds_read2_b32 v[108:109], v10 offset0:8 offset1:41
	ds_read2_b32 v[110:111], v10 offset0:74 offset1:107
	ds_read2_b32 v[112:113], v10 offset0:140 offset1:173
	ds_read2_b32 v[114:115], v10 offset0:206 offset1:239
	ds_read2_b32 v[116:117], v10 offset0:16 offset1:49
	ds_read2_b32 v[118:119], v10 offset0:82 offset1:115
	ds_read2_b32 v[120:121], v10 offset0:148 offset1:181
	ds_read2_b32 v[122:123], v10 offset0:214 offset1:247
	ds_read2_b32 v[124:125], v10 offset0:24 offset1:57
	ds_read2_b32 v[126:127], v10 offset0:90 offset1:123
	ds_read2_b32 v[128:129], v10 offset0:156 offset1:189
	ds_read2_b32 v[130:131], v10 offset0:222 offset1:255
	s_waitcnt lgkmcnt(15)
	v_cvt_pk_bf16_f32 v32, v100, v101
	s_waitcnt lgkmcnt(14)
	v_cvt_pk_bf16_f32 v33, v102, v103
	s_waitcnt lgkmcnt(13)
	v_cvt_pk_bf16_f32 v34, v104, v105
	s_waitcnt lgkmcnt(12)
	v_cvt_pk_bf16_f32 v35, v106, v107
	global_store_dwordx4 v[64:65], v[32:35], off
	v_and_or_b32 v38, v27, s23, v30
	v_ashrrev_i32_e32 v39, 31, v38
	s_waitcnt lgkmcnt(11)
	v_cvt_pk_bf16_f32 v32, v108, v109
	s_waitcnt lgkmcnt(10)
	v_cvt_pk_bf16_f32 v33, v110, v111
	s_waitcnt lgkmcnt(9)
	v_cvt_pk_bf16_f32 v34, v112, v113
	s_waitcnt lgkmcnt(8)
	v_cvt_pk_bf16_f32 v35, v114, v115
	global_store_dwordx4 v[66:67], v[32:35], off
	v_lshlrev_b64 v[38:39], 12, v[38:39]
	v_lshl_add_u64 v[28:29], v[28:29], 0, v[38:39]
	s_waitcnt lgkmcnt(7)
	v_cvt_pk_bf16_f32 v32, v116, v117
	s_waitcnt lgkmcnt(6)
	v_cvt_pk_bf16_f32 v33, v118, v119
	s_waitcnt lgkmcnt(5)
	v_cvt_pk_bf16_f32 v34, v120, v121
	s_waitcnt lgkmcnt(4)
	v_cvt_pk_bf16_f32 v35, v122, v123
	global_store_dwordx4 v[68:69], v[32:35], off
	s_nop 0
	s_waitcnt lgkmcnt(3)
	v_cvt_pk_bf16_f32 v32, v124, v125
	s_waitcnt lgkmcnt(2)
	v_cvt_pk_bf16_f32 v33, v126, v127
	s_waitcnt lgkmcnt(1)
	v_cvt_pk_bf16_f32 v34, v128, v129
	s_waitcnt lgkmcnt(0)
	v_cvt_pk_bf16_f32 v35, v130, v131
	global_store_dwordx4 v[28:29], v[32:35], off
	s_waitcnt lgkmcnt(0)
	s_cbranch_scc1 .LBB0_96
	s_load_dwordx2 s[18:19], s[16:17], 0x80
	s_movk_i32 s5, 0x5800
	v_mov_b32_e32 v3, 0
	s_mov_b32 s8, 0x2c000
	s_mov_b32 s9, 0x58000
	s_waitcnt lgkmcnt(0)
	v_mov_b64_e32 v[8:9], s[18:19]
	s_mov_b32 s18, 0x84000
	s_mov_b32 s19, 0xb0000
	s_mov_b32 s20, 0xdc000
	s_mov_b32 s21, 0x108000
	s_mov_b32 s22, 0x134000
	v_add_u32_e32 v12, 0x420, v11
	v_add_u32_e32 v13, 0x428, v11
	v_add_u32_e32 v14, 0x840, v11
	v_add_u32_e32 v15, 0x848, v11
	v_add_u32_e32 v16, 0xc60, v11
	v_add_u32_e32 v17, 0xc68, v11
	v_add_u32_e32 v18, 0x1080, v11
	v_add_u32_e32 v19, 0x1088, v11
	v_add_u32_e32 v20, 0x14a0, v11
	v_add_u32_e32 v21, 0x14a8, v11
	v_add_u32_e32 v22, 0x18c0, v11
	v_add_u32_e32 v23, 0x18c8, v11
	v_add_u32_e32 v24, 0x1ce0, v11
	v_add_u32_e32 v25, 0x1ce8, v11
	s_movk_i32 s23, 0x80
	s_mov_b32 s24, s6
	s_mov_b32 s25, s11
; __device__ __forceinline__ unsigned cvt_pk_bf16(float lo, float hi) { unsigned r; asm volatile("v_cvt_pk_bf16_f32 %0, %1, %2" : "=v"(r) : "v"(lo), "v"(hi)); return r; }
; #define LAS __attribute__((address_space(3)))
; __device__ __forceinline__ void transpose_item(const float* W, int K, int N, bf16_t* WT, const float* kscale, int kind, LAS float* scr, int item, int lane) {
;     const int nblk = N / 32, kb = item / nblk, nb = item % nblk, k0 = 64 * kb, n0 = 32 * nb;
;     {
;         const float* src = W + (size_t)(k0 + (lane >> 3)) * N + n0 + (lane & 7) * 4;
;         f32x4 t[8];
; #pragma unroll
;         for (int i = 0; i < 8; ++i) t[i] = *(const f32x4*)(src + (size_t)(8 * i) * N);
; #pragma unroll
;         for (int i = 0; i < 8; ++i) {
;             const int kk = 8 * i + (lane >> 3);
;             f32x4 v = t[i]; if (kscale) v = v * kscale[k0 + kk];
;             LAS float* d = scr + kk * 33 + (lane & 7) * 4;
;             d[0] = v[0]; d[1] = v[1]; d[2] = v[2]; d[3] = v[3];
;         }
;     }
;     asm volatile("s_waitcnt lgkmcnt(0)" ::: "memory");
;     const int c = lane & 7;
; #pragma unroll
;     for (int j = 0; j < 4; ++j) {
;         const int n = (lane >> 3) + 8 * j; const LAS float* s = scr + (8 * c) * 33 + n;
;         int drow; float sc; map_col(kind, n0 + n, drow, sc);
;         u32x4 ov; ov.x = cvt_pk_bf16(s[0 * 33] * sc, s[1 * 33] * sc); ov.y = cvt_pk_bf16(s[2 * 33] * sc, s[3 * 33] * sc); ov.z = cvt_pk_bf16(s[4 * 33] * sc, s[5 * 33] * sc); ov.w = cvt_pk_bf16(s[6 * 33] * sc, s[7 * 33] * sc);
;         *(u32x4*)(WT + (size_t)drow * K + k0 + 8 * c) = ov;
;     }
;     asm volatile("s_waitcnt lgkmcnt(0)" ::: "memory");
;     ...
;             transpose_matrix(p.in[I_WU], DM, FFN, (bf16_t*)(wsw + W0_GU), nullptr, MAP_UP, scr, gw, NGW, lane);
.LBB0_98:
	s_mul_hi_i32 s26, s25, 0x2e8ba2e9
	s_lshr_b32 s27, s26, 31
	s_ashr_i32 s26, s26, 5
	s_add_i32 s27, s26, s27
	s_lshl_b32 s26, s27, 6
	s_mul_i32 s38, s27, 0xffffea00
	s_add_i32 s38, s24, s38
	v_or_b32_e32 v26, s26, v1
	v_mad_i64_i32 v[26:27], s[40:41], v26, s5, v[8:9]
	s_ashr_i32 s39, s38, 31
	v_lshl_add_u64 v[26:27], s[38:39], 2, v[26:27]
	v_lshl_add_u64 v[32:33], v[26:27], 0, v[2:3]
	v_add_co_u32_e32 v60, vcc, s8, v32
	global_load_dwordx4 v[26:29], v[32:33], off
	s_nop 0
	v_addc_co_u32_e32 v61, vcc, 0, v33, vcc
	v_add_co_u32_e32 v62, vcc, s9, v32
	s_mul_i32 s39, s27, 0xffffd400
	s_nop 0
	v_addc_co_u32_e32 v63, vcc, 0, v33, vcc
	v_add_co_u32_e32 v64, vcc, s18, v32
	v_add_u32_e32 v30, s39, v5
	s_nop 0
	v_addc_co_u32_e32 v65, vcc, 0, v33, vcc
	v_add_co_u32_e32 v66, vcc, s19, v32
	s_ashr_i32 s27, s26, 31
	s_nop 0
	v_addc_co_u32_e32 v67, vcc, 0, v33, vcc
	v_add_co_u32_e32 v68, vcc, s20, v32
	s_add_i32 s25, s25, s10
	s_nop 0
	v_addc_co_u32_e32 v69, vcc, 0, v33, vcc
	v_add_co_u32_e32 v70, vcc, s21, v32
	s_add_i32 s24, s24, s7
	s_nop 0
	v_addc_co_u32_e32 v71, vcc, 0, v33, vcc
	v_add_co_u32_e32 v72, vcc, s22, v32
	s_cmpk_lt_i32 s25, 0x1600
	s_nop 0
	v_addc_co_u32_e32 v73, vcc, 0, v33, vcc
	global_load_dwordx4 v[32:35], v[60:61], off
	global_load_dwordx4 v[36:39], v[62:63], off
	global_load_dwordx4 v[40:43], v[64:65], off
	global_load_dwordx4 v[44:47], v[66:67], off
	global_load_dwordx4 v[48:51], v[68:69], off
	global_load_dwordx4 v[52:55], v[70:71], off
	global_load_dwordx4 v[56:59], v[72:73], off
	v_add_u32_e32 v68, s38, v1
	v_and_b32_e32 v62, 0xffffff00, v30
	v_add_u32_e32 v63, 16, v30
	v_and_b32_e32 v65, 0x7f, v68
	v_and_b32_e32 v67, 0xffffff00, v63
	v_add_u32_e32 v63, 16, v68
	v_or3_b32 v62, v65, v62, s23
	v_add_u32_e32 v64, 32, v30
	v_add_u32_e32 v66, 8, v68
	v_and_b32_e32 v65, 0x7f, v63
	v_ashrrev_i32_e32 v63, 31, v62
	v_lshl_add_u64 v[60:61], s[26:27], 1, v[6:7]
	v_and_b32_e32 v69, 0xffffff00, v64
	v_and_b32_e32 v64, 0x7f, v66
	v_lshlrev_b64 v[62:63], 12, v[62:63]
	v_or3_b32 v64, v64, v67, s23
	v_lshl_add_u64 v[62:63], v[60:61], 0, v[62:63]
	v_or3_b32 v66, v65, v69, s23
	v_ashrrev_i32_e32 v65, 31, v64
	v_lshlrev_b64 v[64:65], 12, v[64:65]
	v_lshl_add_u64 v[64:65], v[60:61], 0, v[64:65]
	v_ashrrev_i32_e32 v67, 31, v66
	v_lshlrev_b64 v[66:67], 12, v[66:67]
	v_lshl_add_u64 v[66:67], v[60:61], 0, v[66:67]
	v_add_u32_e32 v30, 48, v30
	v_and_b32_e32 v30, 0xffffff00, v30
	v_add_u32_e32 v5, s4, v5
	s_waitcnt vmcnt(7)
	ds_write2_b32 v11, v26, v27 offset1:1
	ds_write2_b32 v11, v28, v29 offset0:2 offset1:3
	s_waitcnt vmcnt(6)
	ds_write2_b32 v12, v32, v33 offset1:1
	ds_write2_b32 v13, v34, v35 offset1:1
	s_waitcnt vmcnt(5)
	ds_write2_b32 v14, v36, v37 offset1:1
	ds_write2_b32 v15, v38, v39 offset1:1
	s_waitcnt vmcnt(4)
	ds_write2_b32 v16, v40, v41 offset1:1
	ds_write2_b32 v17, v42, v43 offset1:1
	s_waitcnt vmcnt(3)
	ds_write2_b32 v18, v44, v45 offset1:1
	ds_write2_b32 v19, v46, v47 offset1:1
	s_waitcnt vmcnt(2)
	ds_write2_b32 v20, v48, v49 offset1:1
	ds_write2_b32 v21, v50, v51 offset1:1
	s_waitcnt vmcnt(1)
	ds_write2_b32 v22, v52, v53 offset1:1
	ds_write2_b32 v23, v54, v55 offset1:1
	s_waitcnt vmcnt(0)
	ds_write2_b32 v24, v56, v57 offset1:1
	ds_write2_b32 v25, v58, v59 offset1:1
	s_waitcnt lgkmcnt(0)
	ds_read2_b32 v[100:101], v10 offset1:33
	ds_read2_b32 v[102:103], v10 offset0:66 offset1:99
	ds_read2_b32 v[104:105], v10 offset0:132 offset1:165
	ds_read2_b32 v[106:107], v10 offset0:198 offset1:231
	ds_read2_b32 v[108:109], v10 offset0:8 offset1:41
	ds_read2_b32 v[110:111], v10 offset0:74 offset1:107
	ds_read2_b32 v[112:113], v10 offset0:140 offset1:173
	ds_read2_b32 v[114:115], v10 offset0:206 offset1:239
	ds_read2_b32 v[116:117], v10 offset0:16 offset1:49
	ds_read2_b32 v[118:119], v10 offset0:82 offset1:115
	ds_read2_b32 v[120:121], v10 offset0:148 offset1:181
	ds_read2_b32 v[122:123], v10 offset0:214 offset1:247
	ds_read2_b32 v[124:125], v10 offset0:24 offset1:57
	ds_read2_b32 v[126:127], v10 offset0:90 offset1:123
	ds_read2_b32 v[128:129], v10 offset0:156 offset1:189
	ds_read2_b32 v[130:131], v10 offset0:222 offset1:255
	s_waitcnt lgkmcnt(15)
	v_cvt_pk_bf16_f32 v26, v100, v101
	s_waitcnt lgkmcnt(14)
	v_cvt_pk_bf16_f32 v27, v102, v103
	s_waitcnt lgkmcnt(13)
	v_cvt_pk_bf16_f32 v28, v104, v105
	s_waitcnt lgkmcnt(12)
	v_cvt_pk_bf16_f32 v29, v106, v107
	global_store_dwordx4 v[62:63], v[26:29], off
	s_nop 0
	s_waitcnt lgkmcnt(11)
	v_cvt_pk_bf16_f32 v26, v108, v109
	s_waitcnt lgkmcnt(10)
	v_cvt_pk_bf16_f32 v27, v110, v111
	s_waitcnt lgkmcnt(9)
	v_cvt_pk_bf16_f32 v28, v112, v113
	s_waitcnt lgkmcnt(8)
	v_cvt_pk_bf16_f32 v29, v114, v115
	global_store_dwordx4 v[64:65], v[26:29], off
	s_nop 0
	s_waitcnt lgkmcnt(7)
	v_cvt_pk_bf16_f32 v26, v116, v117
	s_waitcnt lgkmcnt(6)
	v_cvt_pk_bf16_f32 v27, v118, v119
	s_waitcnt lgkmcnt(5)
	v_cvt_pk_bf16_f32 v28, v120, v121
	s_waitcnt lgkmcnt(4)
	v_cvt_pk_bf16_f32 v29, v122, v123
	global_store_dwordx4 v[66:67], v[26:29], off
	s_nop 0
	s_waitcnt lgkmcnt(3)
	v_cvt_pk_bf16_f32 v26, v124, v125
	v_add_u32_e32 v32, 24, v68
	v_and_b32_e32 v34, 0x7f, v32
	v_or3_b32 v34, v34, v30, s23
	v_ashrrev_i32_e32 v35, 31, v34
	v_lshlrev_b64 v[34:35], 12, v[34:35]
	s_waitcnt lgkmcnt(2)
	v_cvt_pk_bf16_f32 v27, v126, v127
	v_lshl_add_u64 v[34:35], v[60:61], 0, v[34:35]
	s_waitcnt lgkmcnt(1)
	v_cvt_pk_bf16_f32 v28, v128, v129
	s_waitcnt lgkmcnt(0)
	v_cvt_pk_bf16_f32 v29, v130, v131
	global_store_dwordx4 v[34:35], v[26:29], off
	s_waitcnt lgkmcnt(0)
	s_cbranch_scc1 .LBB0_98
	s_load_dwordx2 s[4:5], s[16:17], 0x88
	v_lshlrev_b32_e32 v6, 1, v4
	v_mov_b32_e32 v7, 0
	v_lshl_add_u64 v[4:5], s[14:15], 0, v[6:7]
	s_mov_b64 s[8:9], 0x5830000
	v_lshl_add_u64 v[4:5], v[4:5], 0, s[8:9]
	v_mov_b32_e32 v3, v7
	s_mov_b32 s8, 0x10000
	s_mov_b32 s9, 0x20000
	s_mov_b32 s18, 0x30000
	s_mov_b32 s19, 0x40000
	s_mov_b32 s20, 0x50000
	s_mov_b32 s21, 0x60000
	s_mov_b32 s22, 0x70000
	v_add_u32_e32 v6, 0x420, v11
	v_add_u32_e32 v7, 0x428, v11
	v_add_u32_e32 v8, 0x840, v11
	v_add_u32_e32 v9, 0x848, v11
	v_add_u32_e32 v12, 0xc60, v11
	v_add_u32_e32 v13, 0xc68, v11
	v_add_u32_e32 v14, 0x1080, v11
	v_add_u32_e32 v15, 0x1088, v11
	v_add_u32_e32 v16, 0x14a0, v11
	v_add_u32_e32 v17, 0x14a8, v11
	v_add_u32_e32 v18, 0x18c0, v11
	v_add_u32_e32 v19, 0x18c8, v11
	v_add_u32_e32 v20, 0x1ce0, v11
	v_add_u32_e32 v21, 0x1ce8, v11
	s_movk_i32 s23, 0x2c00
; __device__ __forceinline__ unsigned cvt_pk_bf16(float lo, float hi) { unsigned r; asm volatile("v_cvt_pk_bf16_f32 %0, %1, %2" : "=v"(r) : "v"(lo), "v"(hi)); return r; }
; #define LAS __attribute__((address_space(3)))
; __device__ __forceinline__ void transpose_item(const float* W, int K, int N, bf16_t* WT, const float* kscale, int kind, LAS float* scr, int item, int lane) {
;     const int nblk = N / 32, kb = item / nblk, nb = item % nblk, k0 = 64 * kb, n0 = 32 * nb;
;     {
;         const float* src = W + (size_t)(k0 + (lane >> 3)) * N + n0 + (lane & 7) * 4;
;         f32x4 t[8];
; #pragma unroll
;         for (int i = 0; i < 8; ++i) t[i] = *(const f32x4*)(src + (size_t)(8 * i) * N);
; #pragma unroll
;         for (int i = 0; i < 8; ++i) {
;             const int kk = 8 * i + (lane >> 3);
;             f32x4 v = t[i]; if (kscale) v = v * kscale[k0 + kk];
;             LAS float* d = scr + kk * 33 + (lane & 7) * 4;
;             d[0] = v[0]; d[1] = v[1]; d[2] = v[2]; d[3] = v[3];
;         }
;     }
;     asm volatile("s_waitcnt lgkmcnt(0)" ::: "memory");
;     const int c = lane & 7;
; #pragma unroll
;     for (int j = 0; j < 4; ++j) {
;         const int n = (lane >> 3) + 8 * j; const LAS float* s = scr + (8 * c) * 33 + n;
;         int drow; float sc; map_col(kind, n0 + n, drow, sc);
;         u32x4 ov; ov.x = cvt_pk_bf16(s[0 * 33] * sc, s[1 * 33] * sc); ov.y = cvt_pk_bf16(s[2 * 33] * sc, s[3 * 33] * sc); ov.z = cvt_pk_bf16(s[4 * 33] * sc, s[5 * 33] * sc); ov.w = cvt_pk_bf16(s[6 * 33] * sc, s[7 * 33] * sc);
;         *(u32x4*)(WT + (size_t)drow * K + k0 + 8 * c) = ov;
;     }
;     asm volatile("s_waitcnt lgkmcnt(0)" ::: "memory");
;     ...
;             transpose_matrix(p.in[I_WD], FFN, DM, (bf16_t*)(wsw + W0_DN), nullptr, MAP_ID, scr, gw, NGW, lane);
.LBB0_100:
	s_ashr_i32 s24, s11, 31
	s_lshr_b32 s24, s24, 26
	s_add_i32 s25, s11, s24
	s_and_b32 s24, s25, 0xffffffc0
	s_lshl_b32 s25, s25, 5
	v_or_b32_e32 v22, s24, v1
	s_and_b32 s25, s25, 0xfffff800
	v_ashrrev_i32_e32 v23, 31, v22
	s_sub_i32 s26, s6, s25
	v_lshlrev_b64 v[22:23], 13, v[22:23]
	s_ashr_i32 s27, s26, 31
	s_waitcnt lgkmcnt(0)
	v_lshl_add_u64 v[22:23], s[4:5], 0, v[22:23]
	v_lshl_add_u64 v[22:23], s[26:27], 2, v[22:23]
	v_lshl_add_u64 v[26:27], v[22:23], 0, v[2:3]
	v_add_co_u32_e32 v56, vcc, s8, v26
	global_load_dwordx4 v[22:25], v[26:27], off
	s_nop 0
	v_addc_co_u32_e32 v57, vcc, 0, v27, vcc
	v_add_co_u32_e32 v58, vcc, s9, v26
	s_ashr_i32 s25, s24, 31
	s_nop 0
	v_addc_co_u32_e32 v59, vcc, 0, v27, vcc
	v_add_co_u32_e32 v60, vcc, s18, v26
	v_add_u32_e32 v30, s26, v1
	s_nop 0
	v_addc_co_u32_e32 v61, vcc, 0, v27, vcc
	v_add_co_u32_e32 v62, vcc, s19, v26
	s_add_i32 s11, s11, s10
	s_nop 0
	v_addc_co_u32_e32 v63, vcc, 0, v27, vcc
	v_add_co_u32_e32 v64, vcc, s20, v26
	s_add_i32 s6, s6, s7
	s_nop 0
	v_addc_co_u32_e32 v65, vcc, 0, v27, vcc
	v_add_co_u32_e32 v66, vcc, s21, v26
	s_cmpk_lt_i32 s11, 0x1600
	s_nop 0
	v_addc_co_u32_e32 v67, vcc, 0, v27, vcc
	v_add_co_u32_e32 v68, vcc, s22, v26
	s_nop 1
	v_addc_co_u32_e32 v69, vcc, 0, v27, vcc
	global_load_dwordx4 v[26:29], v[56:57], off
	global_load_dwordx4 v[32:35], v[58:59], off
	global_load_dwordx4 v[36:39], v[60:61], off
	global_load_dwordx4 v[40:43], v[62:63], off
	global_load_dwordx4 v[44:47], v[64:65], off
	global_load_dwordx4 v[48:51], v[66:67], off
	global_load_dwordx4 v[52:55], v[68:69], off
	v_lshl_add_u64 v[56:57], s[24:25], 1, v[4:5]
	v_mad_i64_i32 v[58:59], s[24:25], v30, s23, v[56:57]
	v_add_u32_e32 v60, 8, v30
	v_mad_i64_i32 v[60:61], s[24:25], v60, s23, v[56:57]
	v_add_u32_e32 v62, 16, v30
	v_mad_i64_i32 v[62:63], s[24:25], v62, s23, v[56:57]
	s_waitcnt vmcnt(7)
	ds_write2_b32 v11, v22, v23 offset1:1
	ds_write2_b32 v11, v24, v25 offset0:2 offset1:3
	s_waitcnt vmcnt(6)
	ds_write2_b32 v6, v26, v27 offset1:1
	ds_write2_b32 v7, v28, v29 offset1:1
	s_waitcnt vmcnt(5)
	ds_write2_b32 v8, v32, v33 offset1:1
	ds_write2_b32 v9, v34, v35 offset1:1
	s_waitcnt vmcnt(4)
	ds_write2_b32 v12, v36, v37 offset1:1
	ds_write2_b32 v13, v38, v39 offset1:1
	s_waitcnt vmcnt(3)
	ds_write2_b32 v14, v40, v41 offset1:1
	ds_write2_b32 v15, v42, v43 offset1:1
	s_waitcnt vmcnt(2)
	ds_write2_b32 v16, v44, v45 offset1:1
	ds_write2_b32 v17, v46, v47 offset1:1
	s_waitcnt vmcnt(1)
	ds_write2_b32 v18, v48, v49 offset1:1
	ds_write2_b32 v19, v50, v51 offset1:1
	s_waitcnt vmcnt(0)
	ds_write2_b32 v20, v52, v53 offset1:1
	ds_write2_b32 v21, v54, v55 offset1:1
	s_waitcnt lgkmcnt(0)
	ds_read2_b32 v[100:101], v10 offset1:33
	ds_read2_b32 v[102:103], v10 offset0:66 offset1:99
	ds_read2_b32 v[104:105], v10 offset0:132 offset1:165
	ds_read2_b32 v[106:107], v10 offset0:198 offset1:231
	ds_read2_b32 v[108:109], v10 offset0:8 offset1:41
	ds_read2_b32 v[110:111], v10 offset0:74 offset1:107
	ds_read2_b32 v[112:113], v10 offset0:140 offset1:173
	ds_read2_b32 v[114:115], v10 offset0:206 offset1:239
	ds_read2_b32 v[116:117], v10 offset0:16 offset1:49
	ds_read2_b32 v[118:119], v10 offset0:82 offset1:115
	ds_read2_b32 v[120:121], v10 offset0:148 offset1:181
	ds_read2_b32 v[122:123], v10 offset0:214 offset1:247
	ds_read2_b32 v[124:125], v10 offset0:24 offset1:57
	ds_read2_b32 v[126:127], v10 offset0:90 offset1:123
	ds_read2_b32 v[128:129], v10 offset0:156 offset1:189
	ds_read2_b32 v[130:131], v10 offset0:222 offset1:255
	s_waitcnt lgkmcnt(15)
	v_cvt_pk_bf16_f32 v22, v100, v101
	s_waitcnt lgkmcnt(14)
	v_cvt_pk_bf16_f32 v23, v102, v103
	s_waitcnt lgkmcnt(13)
	v_cvt_pk_bf16_f32 v24, v104, v105
	s_waitcnt lgkmcnt(12)
	v_cvt_pk_bf16_f32 v25, v106, v107
	global_store_dwordx4 v[58:59], v[22:25], off
	s_nop 0
	s_waitcnt lgkmcnt(11)
	v_cvt_pk_bf16_f32 v22, v108, v109
	s_waitcnt lgkmcnt(10)
	v_cvt_pk_bf16_f32 v23, v110, v111
	s_waitcnt lgkmcnt(9)
	v_cvt_pk_bf16_f32 v24, v112, v113
	s_waitcnt lgkmcnt(8)
	v_cvt_pk_bf16_f32 v25, v114, v115
	global_store_dwordx4 v[60:61], v[22:25], off
	s_nop 0
	s_waitcnt lgkmcnt(7)
	v_cvt_pk_bf16_f32 v22, v116, v117
	s_waitcnt lgkmcnt(6)
	v_cvt_pk_bf16_f32 v23, v118, v119
	s_waitcnt lgkmcnt(5)
	v_cvt_pk_bf16_f32 v24, v120, v121
	s_waitcnt lgkmcnt(4)
	v_cvt_pk_bf16_f32 v25, v122, v123
	global_store_dwordx4 v[62:63], v[22:25], off
	s_nop 0
	s_waitcnt lgkmcnt(3)
	v_cvt_pk_bf16_f32 v22, v124, v125
	s_waitcnt lgkmcnt(2)
	v_cvt_pk_bf16_f32 v23, v126, v127
	s_waitcnt lgkmcnt(1)
	v_cvt_pk_bf16_f32 v24, v128, v129
	v_add_u32_e32 v25, 24, v30
	v_mad_i64_i32 v[28:29], s[24:25], v25, s23, v[56:57]
	s_waitcnt lgkmcnt(0)
	v_cvt_pk_bf16_f32 v25, v130, v131
	global_store_dwordx4 v[28:29], v[22:25], off
	s_waitcnt lgkmcnt(0)
	s_cbranch_scc1 .LBB0_100

; __device__ __forceinline__ unsigned cvt_pk_bf16(float lo, float hi) { unsigned r; asm volatile("v_cvt_pk_bf16_f32 %0, %1, %2" : "=v"(r) : "v"(lo), "v"(hi)); return r; }
; #define LAS __attribute__((address_space(3)))
; __device__ __forceinline__ void transpose_item(const float* W, int K, int N, bf16_t* WT, const float* kscale, int kind, LAS float* scr, int item, int lane) {
;     const int nblk = N / 32, kb = item / nblk, nb = item % nblk, k0 = 64 * kb, n0 = 32 * nb;
;     {
;         const float* src = W + (size_t)(k0 + (lane >> 3)) * N + n0 + (lane & 7) * 4;
;         f32x4 t[8];
; #pragma unroll
;         for (int i = 0; i < 8; ++i) t[i] = *(const f32x4*)(src + (size_t)(8 * i) * N);
; #pragma unroll
;         for (int i = 0; i < 8; ++i) {
;             const int kk = 8 * i + (lane >> 3);
;             f32x4 v = t[i]; if (kscale) v = v * kscale[k0 + kk];
;             LAS float* d = scr + kk * 33 + (lane & 7) * 4;
;             d[0] = v[0]; d[1] = v[1]; d[2] = v[2]; d[3] = v[3];
;         }
;     }
;     asm volatile("s_waitcnt lgkmcnt(0)" ::: "memory");
;     const int c = lane & 7;
; #pragma unroll
;     for (int j = 0; j < 4; ++j) {
;         const int n = (lane >> 3) + 8 * j; const LAS float* s = scr + (8 * c) * 33 + n;
;         int drow; float sc; map_col(kind, n0 + n, drow, sc);
;         u32x4 ov; ov.x = cvt_pk_bf16(s[0 * 33] * sc, s[1 * 33] * sc); ov.y = cvt_pk_bf16(s[2 * 33] * sc, s[3 * 33] * sc); ov.z = cvt_pk_bf16(s[4 * 33] * sc, s[5 * 33] * sc); ov.w = cvt_pk_bf16(s[6 * 33] * sc, s[7 * 33] * sc);
;         *(u32x4*)(WT + (size_t)drow * K + k0 + 8 * c) = ov;
;     }
;     asm volatile("s_waitcnt lgkmcnt(0)" ::: "memory");
;     ...
;                 transpose_matrix(p.in[I_MW_IN], DM, 1088, wm, nullptr, MAP_WM, scr, gw, NGW, lane);
.LBB0_760:
	s_mul_hi_i32 s4, s41, 0x78787879
	s_lshr_b32 s5, s4, 31
	s_ashr_i32 s4, s4, 4
	s_add_i32 s5, s4, s5
	s_lshl_b32 s4, s5, 6
	s_mul_i32 s6, s5, 0xfffffbc0
	s_add_i32 s6, s9, s6
	v_or_b32_e32 v25, s4, v48
	v_mad_i64_i32 v[26:27], s[42:43], v25, s20, v[4:5]
	s_ashr_i32 s7, s6, 31
	v_lshl_add_u64 v[26:27], s[6:7], 2, v[26:27]
	v_lshl_add_u64 v[30:31], v[26:27], 0, v[0:1]
	v_add_co_u32_e32 v46, vcc, s21, v30
	global_load_dwordx4 v[26:29], v[30:31], off
	s_nop 0
	v_addc_co_u32_e32 v47, vcc, 0, v31, vcc
	v_add_co_u32_e32 v62, vcc, s22, v30
	v_add_u32_e32 v25, s6, v48
	s_nop 0
	v_addc_co_u32_e32 v63, vcc, 0, v31, vcc
	v_add_co_u32_e32 v64, vcc, s23, v30
	s_mul_i32 s7, s5, 0x880
	s_nop 0
	v_addc_co_u32_e32 v65, vcc, 0, v31, vcc
	v_add_co_u32_e32 v66, vcc, s24, v30
	s_ashr_i32 s5, s4, 31
	s_nop 0
	v_addc_co_u32_e32 v67, vcc, 0, v31, vcc
	v_add_co_u32_e32 v68, vcc, s25, v30
	s_add_i32 s41, s41, s12
	s_nop 0
	v_addc_co_u32_e32 v69, vcc, 0, v31, vcc
	v_add_co_u32_e32 v70, vcc, s26, v30
	s_add_i32 s9, s9, s13
	s_nop 0
	v_addc_co_u32_e32 v71, vcc, 0, v31, vcc
	v_add_co_u32_e32 v72, vcc, s27, v30
	s_cmpk_lt_i32 s41, 0x440
	s_nop 0
	v_addc_co_u32_e32 v73, vcc, 0, v31, vcc
	global_load_dwordx4 v[30:33], v[46:47], off offset:2048
	global_load_dwordx4 v[34:37], v[62:63], off
	global_load_dwordx4 v[38:41], v[64:65], off offset:2048
	global_load_dwordx4 v[42:45], v[66:67], off
	global_load_dwordx4 v[50:53], v[68:69], off offset:2048
	global_load_dwordx4 v[54:57], v[70:71], off
	global_load_dwordx4 v[58:61], v[72:73], off offset:2048
	v_cmp_gt_u32_e32 vcc, s8, v25
	v_add_u32_e32 v64, 8, v25
	v_add_u32_e32 v65, 16, v25
	v_cndmask_b32_e32 v62, v23, v24, vcc
	v_cmp_gt_u32_e32 vcc, s8, v64
	v_subrev_u32_e32 v62, s7, v62
	v_add3_u32 v62, v7, v62, s39
	v_cndmask_b32_e32 v63, v23, v24, vcc
	v_cmp_gt_u32_e32 vcc, s8, v65
	v_subrev_u32_e32 v63, s7, v63
	v_add_u32_e32 v68, 24, v25
	v_cndmask_b32_e32 v66, v23, v24, vcc
	v_cmp_lt_i32_e32 vcc, s38, v25
	v_lshl_add_u64 v[46:47], s[4:5], 1, v[2:3]
	v_subrev_u32_e32 v66, s7, v66
	v_cndmask_b32_e32 v62, v25, v62, vcc
	v_add3_u32 v25, v7, v63, s40
	v_ashrrev_i32_e32 v63, 31, v62
	v_cmp_lt_i32_e32 vcc, s38, v64
	v_lshlrev_b64 v[62:63], 12, v[62:63]
	v_add3_u32 v66, v7, v66, -16
	v_cmp_lt_i32_e64 s[4:5], s38, v65
	v_cndmask_b32_e32 v64, v64, v25, vcc
	v_lshl_add_u64 v[62:63], v[46:47], 0, v[62:63]
	v_cndmask_b32_e64 v66, v65, v66, s[4:5]
	v_ashrrev_i32_e32 v65, 31, v64
	v_cmp_gt_u32_e32 vcc, s8, v68
	v_lshlrev_b64 v[64:65], 12, v[64:65]
	v_lshl_add_u64 v[64:65], v[46:47], 0, v[64:65]
	v_cndmask_b32_e32 v25, v23, v24, vcc
	v_subrev_u32_e32 v25, s7, v25
	v_ashrrev_i32_e32 v67, 31, v66
	v_add_u32_e32 v25, v7, v25
	v_cmp_lt_i32_e32 vcc, s38, v68
	v_lshlrev_b64 v[66:67], 12, v[66:67]
	v_lshl_add_u64 v[66:67], v[46:47], 0, v[66:67]
	v_add_u32_e32 v7, s17, v7
	s_waitcnt vmcnt(7)
	ds_write2_b32 v8, v26, v27 offset1:1
	ds_write2_b32 v8, v28, v29 offset0:2 offset1:3
	s_waitcnt vmcnt(6)
	ds_write2_b32 v9, v30, v31 offset1:1
	ds_write2_b32 v10, v32, v33 offset1:1
	s_waitcnt vmcnt(5)
	ds_write2_b32 v11, v34, v35 offset1:1
	ds_write2_b32 v12, v36, v37 offset1:1
	s_waitcnt vmcnt(4)
	ds_write2_b32 v13, v38, v39 offset1:1
	ds_write2_b32 v14, v40, v41 offset1:1
	s_waitcnt vmcnt(3)
	ds_write2_b32 v15, v42, v43 offset1:1
	ds_write2_b32 v16, v44, v45 offset1:1
	s_waitcnt vmcnt(2)
	ds_write2_b32 v17, v50, v51 offset1:1
	ds_write2_b32 v18, v52, v53 offset1:1
	s_waitcnt vmcnt(1)
	ds_write2_b32 v19, v54, v55 offset1:1
	ds_write2_b32 v20, v56, v57 offset1:1
	s_waitcnt vmcnt(0)
	ds_write2_b32 v21, v58, v59 offset1:1
	ds_write2_b32 v22, v60, v61 offset1:1
	s_waitcnt lgkmcnt(0)
	ds_read2_b32 v[100:101], v6 offset1:33
	ds_read2_b32 v[102:103], v6 offset0:66 offset1:99
	ds_read2_b32 v[104:105], v6 offset0:132 offset1:165
	ds_read2_b32 v[106:107], v6 offset0:198 offset1:231
	ds_read2_b32 v[108:109], v6 offset0:8 offset1:41
	ds_read2_b32 v[110:111], v6 offset0:74 offset1:107
	ds_read2_b32 v[112:113], v6 offset0:140 offset1:173
	ds_read2_b32 v[114:115], v6 offset0:206 offset1:239
	ds_read2_b32 v[116:117], v6 offset0:16 offset1:49
	ds_read2_b32 v[118:119], v6 offset0:82 offset1:115
	ds_read2_b32 v[120:121], v6 offset0:148 offset1:181
	ds_read2_b32 v[122:123], v6 offset0:214 offset1:247
	ds_read2_b32 v[124:125], v6 offset0:24 offset1:57
	ds_read2_b32 v[126:127], v6 offset0:90 offset1:123
	ds_read2_b32 v[128:129], v6 offset0:156 offset1:189
	ds_read2_b32 v[130:131], v6 offset0:222 offset1:255
	s_waitcnt lgkmcnt(15)
	v_cvt_pk_bf16_f32 v26, v100, v101
	s_waitcnt lgkmcnt(14)
	v_cvt_pk_bf16_f32 v27, v102, v103
	s_waitcnt lgkmcnt(13)
	v_cvt_pk_bf16_f32 v28, v104, v105
	s_waitcnt lgkmcnt(12)
	v_cvt_pk_bf16_f32 v29, v106, v107
	global_store_dwordx4 v[62:63], v[26:29], off
	v_cndmask_b32_e32 v32, v68, v25, vcc
	v_ashrrev_i32_e32 v33, 31, v32
	s_waitcnt lgkmcnt(11)
	v_cvt_pk_bf16_f32 v26, v108, v109
	s_waitcnt lgkmcnt(10)
	v_cvt_pk_bf16_f32 v27, v110, v111
	s_waitcnt lgkmcnt(9)
	v_cvt_pk_bf16_f32 v28, v112, v113
	s_waitcnt lgkmcnt(8)
	v_cvt_pk_bf16_f32 v29, v114, v115
	global_store_dwordx4 v[64:65], v[26:29], off
	v_lshlrev_b64 v[32:33], 12, v[32:33]
	v_lshl_add_u64 v[32:33], v[46:47], 0, v[32:33]
	s_waitcnt lgkmcnt(7)
	v_cvt_pk_bf16_f32 v26, v116, v117
	s_waitcnt lgkmcnt(6)
	v_cvt_pk_bf16_f32 v27, v118, v119
	s_waitcnt lgkmcnt(5)
	v_cvt_pk_bf16_f32 v28, v120, v121
	s_waitcnt lgkmcnt(4)
	v_cvt_pk_bf16_f32 v29, v122, v123
	global_store_dwordx4 v[66:67], v[26:29], off
	s_nop 0
	s_waitcnt lgkmcnt(3)
	v_cvt_pk_bf16_f32 v26, v124, v125
	s_waitcnt lgkmcnt(2)
	v_cvt_pk_bf16_f32 v27, v126, v127
	s_waitcnt lgkmcnt(1)
	v_cvt_pk_bf16_f32 v28, v128, v129
	s_waitcnt lgkmcnt(0)
	v_cvt_pk_bf16_f32 v29, v130, v131
	global_store_dwordx4 v[32:33], v[26:29], off
	s_waitcnt lgkmcnt(0)
	s_cbranch_scc1 .LBB0_760

; __device__ __forceinline__ unsigned cvt_pk_bf16(float lo, float hi) { unsigned r; asm volatile("v_cvt_pk_bf16_f32 %0, %1, %2" : "=v"(r) : "v"(lo), "v"(hi)); return r; }
; #define LAS __attribute__((address_space(3)))
; __device__ __forceinline__ void transpose_item(const float* W, int K, int N, bf16_t* WT, const float* kscale, int kind, LAS float* scr, int item, int lane) {
;     const int nblk = N / 32, kb = item / nblk, nb = item % nblk, k0 = 64 * kb, n0 = 32 * nb;
;     {
;         const float* src = W + (size_t)(k0 + (lane >> 3)) * N + n0 + (lane & 7) * 4;
;         f32x4 t[8];
; #pragma unroll
;         for (int i = 0; i < 8; ++i) t[i] = *(const f32x4*)(src + (size_t)(8 * i) * N);
; #pragma unroll
;         for (int i = 0; i < 8; ++i) {
;             const int kk = 8 * i + (lane >> 3);
;             f32x4 v = t[i]; if (kscale) v = v * kscale[k0 + kk];
;             LAS float* d = scr + kk * 33 + (lane & 7) * 4;
;             d[0] = v[0]; d[1] = v[1]; d[2] = v[2]; d[3] = v[3];
;         }
;     }
;     asm volatile("s_waitcnt lgkmcnt(0)" ::: "memory");
;     const int c = lane & 7;
; #pragma unroll
;     for (int j = 0; j < 4; ++j) {
;         const int n = (lane >> 3) + 8 * j; const LAS float* s = scr + (8 * c) * 33 + n;
;         int drow; float sc; map_col(kind, n0 + n, drow, sc);
;         u32x4 ov; ov.x = cvt_pk_bf16(s[0 * 33] * sc, s[1 * 33] * sc); ov.y = cvt_pk_bf16(s[2 * 33] * sc, s[3 * 33] * sc); ov.z = cvt_pk_bf16(s[4 * 33] * sc, s[5 * 33] * sc); ov.w = cvt_pk_bf16(s[6 * 33] * sc, s[7 * 33] * sc);
;         *(u32x4*)(WT + (size_t)drow * K + k0 + 8 * c) = ov;
;     }
;     asm volatile("s_waitcnt lgkmcnt(0)" ::: "memory");
;     ...
;                 transpose_matrix(p.in[I_WKVUP], 512, 4096, (bf16_t*)(wsw + W1_KV), p.in[I_KVNG], MAP_ID, scr, gw, NGW, lane);
.LBB0_782:
	s_sub_i32 s22, 0, s21
	s_waitcnt vmcnt(2)
	ds_write2_b32 v60, v14, v15 offset1:1
	ds_write2_b32 v61, v12, v13 offset1:1
	ds_write2_b32 v62, v8, v9 offset1:1
	ds_write2_b32 v63, v10, v11 offset1:1
	s_add_i32 s22, s22, s13
	s_waitcnt lgkmcnt(0)
	v_add_u32_e32 v8, s22, v48
	s_waitcnt vmcnt(1)
	ds_read2_b32 v[100:101], v46 offset1:33
	ds_read2_b32 v[102:103], v46 offset0:66 offset1:99
	ds_read2_b32 v[104:105], v46 offset0:132 offset1:165
	ds_read2_b32 v[106:107], v46 offset0:198 offset1:231
	ds_read2_b32 v[108:109], v46 offset0:8 offset1:41
	ds_read2_b32 v[110:111], v46 offset0:74 offset1:107
	ds_read2_b32 v[112:113], v46 offset0:140 offset1:173
	ds_read2_b32 v[114:115], v46 offset0:206 offset1:239
	ds_read2_b32 v[116:117], v46 offset0:16 offset1:49
	ds_read2_b32 v[118:119], v46 offset0:82 offset1:115
	ds_read2_b32 v[120:121], v46 offset0:148 offset1:181
	ds_read2_b32 v[122:123], v46 offset0:214 offset1:247
	ds_read2_b32 v[124:125], v46 offset0:24 offset1:57
	ds_read2_b32 v[126:127], v46 offset0:90 offset1:123
	ds_read2_b32 v[128:129], v46 offset0:156 offset1:189
	ds_read2_b32 v[130:131], v46 offset0:222 offset1:255
	s_ashr_i32 s21, s20, 31
	v_ashrrev_i32_e32 v9, 31, v8
	s_waitcnt lgkmcnt(15)
	v_cvt_pk_bf16_f32 v0, v100, v101
	s_waitcnt vmcnt(0)
	v_lshl_add_u64 v[6:7], s[20:21], 1, v[38:39]
	v_lshlrev_b64 v[10:11], 10, v[8:9]
	s_waitcnt lgkmcnt(14)
	v_cvt_pk_bf16_f32 v1, v102, v103
	v_lshl_add_u64 v[10:11], v[6:7], 0, v[10:11]
	s_waitcnt lgkmcnt(13)
	v_cvt_pk_bf16_f32 v2, v104, v105
	s_waitcnt lgkmcnt(12)
	v_cvt_pk_bf16_f32 v3, v106, v107
	global_store_dwordx4 v[10:11], v[0:3], off
	v_add_u32_e32 v10, 8, v8
	v_ashrrev_i32_e32 v11, 31, v10
	s_waitcnt lgkmcnt(11)
	v_cvt_pk_bf16_f32 v0, v108, v109
	v_lshlrev_b64 v[10:11], 10, v[10:11]
	s_waitcnt lgkmcnt(10)
	v_cvt_pk_bf16_f32 v1, v110, v111
	v_lshl_add_u64 v[10:11], v[6:7], 0, v[10:11]
	s_waitcnt lgkmcnt(9)
	v_cvt_pk_bf16_f32 v2, v112, v113
	s_waitcnt lgkmcnt(8)
	v_cvt_pk_bf16_f32 v3, v114, v115
	global_store_dwordx4 v[10:11], v[0:3], off
	v_add_u32_e32 v10, 16, v8
	s_waitcnt lgkmcnt(7)
	v_cvt_pk_bf16_f32 v0, v116, v117
	v_ashrrev_i32_e32 v11, 31, v10
	s_waitcnt lgkmcnt(6)
	v_cvt_pk_bf16_f32 v1, v118, v119
	v_lshlrev_b64 v[10:11], 10, v[10:11]
	v_add_u32_e32 v8, 24, v8
	s_waitcnt lgkmcnt(5)
	v_cvt_pk_bf16_f32 v2, v120, v121
	s_waitcnt lgkmcnt(4)
	v_cvt_pk_bf16_f32 v3, v122, v123
	v_lshl_add_u64 v[10:11], v[6:7], 0, v[10:11]
	v_ashrrev_i32_e32 v9, 31, v8
	global_store_dwordx4 v[10:11], v[0:3], off
	v_lshlrev_b64 v[8:9], 10, v[8:9]
	v_lshl_add_u64 v[6:7], v[6:7], 0, v[8:9]
	s_waitcnt lgkmcnt(3)
	v_cvt_pk_bf16_f32 v0, v124, v125
	s_waitcnt lgkmcnt(2)
	v_cvt_pk_bf16_f32 v1, v126, v127
	s_waitcnt lgkmcnt(1)
	v_cvt_pk_bf16_f32 v2, v128, v129
	s_waitcnt lgkmcnt(0)
	v_cvt_pk_bf16_f32 v3, v130, v131
	global_store_dwordx4 v[6:7], v[0:3], off
	s_waitcnt lgkmcnt(0)
	s_add_i32 s38, s38, s12
	s_add_i32 s13, s13, s17
	s_cmpk_lt_i32 s38, 0x400
	s_cbranch_scc0 .LBB0_799

; __device__ __forceinline__ unsigned cvt_pk_bf16(float lo, float hi) { unsigned r; asm volatile("v_cvt_pk_bf16_f32 %0, %1, %2" : "=v"(r) : "v"(lo), "v"(hi)); return r; }
; #define LAS __attribute__((address_space(3)))
; __device__ __forceinline__ void transpose_item(const float* W, int K, int N, bf16_t* WT, const float* kscale, int kind, LAS float* scr, int item, int lane) {
;     const int nblk = N / 32, kb = item / nblk, nb = item % nblk, k0 = 64 * kb, n0 = 32 * nb;
;     {
;         const float* src = W + (size_t)(k0 + (lane >> 3)) * N + n0 + (lane & 7) * 4;
;         f32x4 t[8];
; #pragma unroll
;         for (int i = 0; i < 8; ++i) t[i] = *(const f32x4*)(src + (size_t)(8 * i) * N);
; #pragma unroll
;         for (int i = 0; i < 8; ++i) {
;             const int kk = 8 * i + (lane >> 3);
;             f32x4 v = t[i]; if (kscale) v = v * kscale[k0 + kk];
;             LAS float* d = scr + kk * 33 + (lane & 7) * 4;
;             d[0] = v[0]; d[1] = v[1]; d[2] = v[2]; d[3] = v[3];
;         }
;     }
;     asm volatile("s_waitcnt lgkmcnt(0)" ::: "memory");
;     const int c = lane & 7;
; #pragma unroll
;     for (int j = 0; j < 4; ++j) {
;         const int n = (lane >> 3) + 8 * j; const LAS float* s = scr + (8 * c) * 33 + n;
;         int drow; float sc; map_col(kind, n0 + n, drow, sc);
;         u32x4 ov; ov.x = cvt_pk_bf16(s[0 * 33] * sc, s[1 * 33] * sc); ov.y = cvt_pk_bf16(s[2 * 33] * sc, s[3 * 33] * sc); ov.z = cvt_pk_bf16(s[4 * 33] * sc, s[5 * 33] * sc); ov.w = cvt_pk_bf16(s[6 * 33] * sc, s[7 * 33] * sc);
;         *(u32x4*)(WT + (size_t)drow * K + k0 + 8 * c) = ov;
;     }
;     asm volatile("s_waitcnt lgkmcnt(0)" ::: "memory");
;     ...
;                 transpose_matrix(p.in[I_MW_OUT], DM, DM, (bf16_t*)(wsw + W1_OUT), nullptr, MAP_ID, scr, gw, NGW, lane);
.LBB0_801:
	s_ashr_i32 s19, s16, 31
	s_lshr_b32 s19, s19, 26
	s_add_i32 s19, s16, s19
	s_and_b32 s20, s19, 0xffffffc0
	s_lshl_b32 s19, s19, 5
	v_or_b32_e32 v20, s20, v48
	s_and_b32 s19, s19, 0xfffff800
	v_ashrrev_i32_e32 v21, 31, v20
	s_sub_i32 s22, s6, s19
	v_lshlrev_b64 v[20:21], 13, v[20:21]
	s_ashr_i32 s23, s22, 31
	v_lshl_add_u64 v[20:21], s[4:5], 0, v[20:21]
	v_lshl_add_u64 v[20:21], s[22:23], 2, v[20:21]
	v_lshl_add_u64 v[24:25], v[20:21], 0, v[0:1]
	v_add_co_u32_e32 v54, vcc, s8, v24
	global_load_dwordx4 v[20:23], v[24:25], off
	s_nop 0
	v_addc_co_u32_e32 v55, vcc, 0, v25, vcc
	v_add_co_u32_e32 v56, vcc, s9, v24
	s_ashr_i32 s21, s20, 31
	s_nop 0
	v_addc_co_u32_e32 v57, vcc, 0, v25, vcc
	v_add_co_u32_e32 v58, vcc, s10, v24
	s_add_i32 s16, s16, s12
	s_nop 0
	v_addc_co_u32_e32 v59, vcc, 0, v25, vcc
	v_add_co_u32_e32 v60, vcc, s11, v24
	s_add_i32 s6, s6, s7
	s_nop 0
	v_addc_co_u32_e32 v61, vcc, 0, v25, vcc
	v_add_co_u32_e32 v62, vcc, s13, v24
	s_cmpk_gt_i32 s16, 0x7ff
	s_nop 0
	v_addc_co_u32_e32 v63, vcc, 0, v25, vcc
	v_add_co_u32_e32 v64, vcc, s17, v24
	s_nop 1
	v_addc_co_u32_e32 v65, vcc, 0, v25, vcc
	v_add_co_u32_e32 v66, vcc, s18, v24
	s_nop 1
	v_addc_co_u32_e32 v67, vcc, 0, v25, vcc
	global_load_dwordx4 v[24:27], v[54:55], off
	global_load_dwordx4 v[28:31], v[56:57], off
	global_load_dwordx4 v[32:35], v[58:59], off
	global_load_dwordx4 v[36:39], v[60:61], off
	global_load_dwordx4 v[40:43], v[62:63], off
	global_load_dwordx4 v[44:47], v[64:65], off
	global_load_dwordx4 v[50:53], v[66:67], off
	v_add_u32_e32 v56, s22, v48
	v_ashrrev_i32_e32 v57, 31, v56
	v_lshl_add_u64 v[54:55], s[20:21], 1, v[2:3]
	v_lshlrev_b64 v[62:63], 12, v[56:57]
	v_add_u32_e32 v58, 8, v56
	v_lshl_add_u64 v[62:63], v[54:55], 0, v[62:63]
	v_ashrrev_i32_e32 v59, 31, v58
	v_lshlrev_b64 v[58:59], 12, v[58:59]
	v_add_u32_e32 v60, 16, v56
	v_lshl_add_u64 v[58:59], v[54:55], 0, v[58:59]
	v_ashrrev_i32_e32 v61, 31, v60
	v_lshlrev_b64 v[60:61], 12, v[60:61]
	v_lshl_add_u64 v[60:61], v[54:55], 0, v[60:61]
	s_waitcnt vmcnt(7)
	ds_write2_b32 v5, v20, v21 offset1:1
	ds_write2_b32 v5, v22, v23 offset0:2 offset1:3
	s_waitcnt vmcnt(6)
	ds_write2_b32 v6, v24, v25 offset1:1
	ds_write2_b32 v7, v26, v27 offset1:1
	s_waitcnt vmcnt(5)
	ds_write2_b32 v8, v28, v29 offset1:1
	ds_write2_b32 v9, v30, v31 offset1:1
	s_waitcnt vmcnt(4)
	ds_write2_b32 v10, v32, v33 offset1:1
	ds_write2_b32 v11, v34, v35 offset1:1
	s_waitcnt vmcnt(3)
	ds_write2_b32 v12, v36, v37 offset1:1
	ds_write2_b32 v13, v38, v39 offset1:1
	s_waitcnt vmcnt(2)
	ds_write2_b32 v14, v40, v41 offset1:1
	ds_write2_b32 v15, v42, v43 offset1:1
	s_waitcnt vmcnt(1)
	ds_write2_b32 v16, v44, v45 offset1:1
	ds_write2_b32 v17, v46, v47 offset1:1
	s_waitcnt vmcnt(0)
	ds_write2_b32 v18, v50, v51 offset1:1
	ds_write2_b32 v19, v52, v53 offset1:1
	s_waitcnt lgkmcnt(0)
	ds_read2_b32 v[100:101], v4 offset1:33
	ds_read2_b32 v[102:103], v4 offset0:66 offset1:99
	ds_read2_b32 v[104:105], v4 offset0:132 offset1:165
	ds_read2_b32 v[106:107], v4 offset0:198 offset1:231
	ds_read2_b32 v[108:109], v4 offset0:8 offset1:41
	ds_read2_b32 v[110:111], v4 offset0:74 offset1:107
	ds_read2_b32 v[112:113], v4 offset0:140 offset1:173
	ds_read2_b32 v[114:115], v4 offset0:206 offset1:239
	ds_read2_b32 v[116:117], v4 offset0:16 offset1:49
	ds_read2_b32 v[118:119], v4 offset0:82 offset1:115
	ds_read2_b32 v[120:121], v4 offset0:148 offset1:181
	ds_read2_b32 v[122:123], v4 offset0:214 offset1:247
	ds_read2_b32 v[124:125], v4 offset0:24 offset1:57
	ds_read2_b32 v[126:127], v4 offset0:90 offset1:123
	ds_read2_b32 v[128:129], v4 offset0:156 offset1:189
	ds_read2_b32 v[130:131], v4 offset0:222 offset1:255
	s_waitcnt lgkmcnt(15)
	v_cvt_pk_bf16_f32 v20, v100, v101
	s_waitcnt lgkmcnt(14)
	v_cvt_pk_bf16_f32 v21, v102, v103
	s_waitcnt lgkmcnt(13)
	v_cvt_pk_bf16_f32 v22, v104, v105
	s_waitcnt lgkmcnt(12)
	v_cvt_pk_bf16_f32 v23, v106, v107
	global_store_dwordx4 v[62:63], v[20:23], off
	v_add_u32_e32 v26, 24, v56
	v_ashrrev_i32_e32 v27, 31, v26
	s_waitcnt lgkmcnt(11)
	v_cvt_pk_bf16_f32 v20, v108, v109
	s_waitcnt lgkmcnt(10)
	v_cvt_pk_bf16_f32 v21, v110, v111
	s_waitcnt lgkmcnt(9)
	v_cvt_pk_bf16_f32 v22, v112, v113
	s_waitcnt lgkmcnt(8)
	v_cvt_pk_bf16_f32 v23, v114, v115
	global_store_dwordx4 v[58:59], v[20:23], off
	v_lshlrev_b64 v[26:27], 12, v[26:27]
	v_lshl_add_u64 v[26:27], v[54:55], 0, v[26:27]
	s_waitcnt lgkmcnt(7)
	v_cvt_pk_bf16_f32 v20, v116, v117
	s_waitcnt lgkmcnt(6)
	v_cvt_pk_bf16_f32 v21, v118, v119
	s_waitcnt lgkmcnt(5)
	v_cvt_pk_bf16_f32 v22, v120, v121
	s_waitcnt lgkmcnt(4)
	v_cvt_pk_bf16_f32 v23, v122, v123
	global_store_dwordx4 v[60:61], v[20:23], off
	s_nop 0
	s_waitcnt lgkmcnt(3)
	v_cvt_pk_bf16_f32 v20, v124, v125
	s_waitcnt lgkmcnt(2)
	v_cvt_pk_bf16_f32 v21, v126, v127
	s_waitcnt lgkmcnt(1)
	v_cvt_pk_bf16_f32 v22, v128, v129
	s_waitcnt lgkmcnt(0)
	v_cvt_pk_bf16_f32 v23, v130, v131
	global_store_dwordx4 v[26:27], v[20:23], off
	s_waitcnt lgkmcnt(0)
	s_cbranch_scc0 .LBB0_801

; __device__ __forceinline__ unsigned cvt_pk_bf16(float lo, float hi) { unsigned r; asm volatile("v_cvt_pk_bf16_f32 %0, %1, %2" : "=v"(r) : "v"(lo), "v"(hi)); return r; }
; #define LAS __attribute__((address_space(3)))
; __device__ __forceinline__ void transpose_item(const float* W, int K, int N, bf16_t* WT, const float* kscale, int kind, LAS float* scr, int item, int lane) {
;     const int nblk = N / 32, kb = item / nblk, nb = item % nblk, k0 = 64 * kb, n0 = 32 * nb;
;     {
;         const float* src = W + (size_t)(k0 + (lane >> 3)) * N + n0 + (lane & 7) * 4;
;         f32x4 t[8];
; #pragma unroll
;         for (int i = 0; i < 8; ++i) t[i] = *(const f32x4*)(src + (size_t)(8 * i) * N);
; #pragma unroll
;         for (int i = 0; i < 8; ++i) {
;             const int kk = 8 * i + (lane >> 3);
;             f32x4 v = t[i]; if (kscale) v = v * kscale[k0 + kk];
;             LAS float* d = scr + kk * 33 + (lane & 7) * 4;
;             d[0] = v[0]; d[1] = v[1]; d[2] = v[2]; d[3] = v[3];
;         }
;     }
;     asm volatile("s_waitcnt lgkmcnt(0)" ::: "memory");
;     const int c = lane & 7;
; #pragma unroll
;     for (int j = 0; j < 4; ++j) {
;         const int n = (lane >> 3) + 8 * j; const LAS float* s = scr + (8 * c) * 33 + n;
;         int drow; float sc; map_col(kind, n0 + n, drow, sc);
;         u32x4 ov; ov.x = cvt_pk_bf16(s[0 * 33] * sc, s[1 * 33] * sc); ov.y = cvt_pk_bf16(s[2 * 33] * sc, s[3 * 33] * sc); ov.z = cvt_pk_bf16(s[4 * 33] * sc, s[5 * 33] * sc); ov.w = cvt_pk_bf16(s[6 * 33] * sc, s[7 * 33] * sc);
;         *(u32x4*)(WT + (size_t)drow * K + k0 + 8 * c) = ov;
;     }
;     asm volatile("s_waitcnt lgkmcnt(0)" ::: "memory");
; template <bool DRAIN>
; __device__ __forceinline__ void bg_convert(const float* wg1, const float* wu1, const float* wd1, unsigned char* wsw, unsigned* ctl, int done_word, int G, LAS float* scr, int lane) {
;     ...
;         for (int i = i0; i < i0 + 4; ++i) {
;             const int m = i / BG_ITEMS_PER, it = i - m * BG_ITEMS_PER;
;             if (m == 0) transpose_item(wg1, DM, FFN, (bf16_t*)(wsw + W1_GU), nullptr, MAP_GATE, scr, it, lane);
;             else if (m == 1) transpose_item(wu1, DM, FFN, (bf16_t*)(wsw + W1_GU), nullptr, MAP_UP, scr, it, lane);
;             else transpose_item(wd1, FFN, DM, (bf16_t*)(wsw + W1_DN), nullptr, MAP_ID, scr, it, lane);
.LBB0_918:
	s_add_i32 s16, s20, 0xffffea00
	s_cmpk_gt_u32 s16, 0x15ff
	s_cbranch_scc0 .LBB0_920
	s_sext_i32_i16 s16, s22
	s_bfe_u32 s16, s16, 0x60019
	s_add_i32 s16, s22, s16
	s_sext_i32_i16 s18, s16
	s_and_b32 s16, s16, 0xffc0
	s_and_b32 s54, s18, 0xffffffc0
	s_sub_i32 s16, s22, s16
	v_or_b32_e32 v30, s54, v6
	s_sext_i32_i16 s16, s16
	v_ashrrev_i32_e32 v31, 31, v30
	s_lshl_b32 s18, s16, 5
	v_lshlrev_b64 v[30:31], 13, v[30:31]
	v_lshl_add_u64 v[30:31], s[10:11], 0, v[30:31]
	s_ashr_i32 s19, s18, 31
	v_lshl_add_u64 v[30:31], s[18:19], 2, v[30:31]
	v_lshl_add_u64 v[58:59], v[30:31], 0, v[0:1]
	v_add_co_u32_e32 v34, vcc, s24, v58
	s_ashr_i32 s55, s54, 31
	s_nop 0
	v_addc_co_u32_e32 v35, vcc, 0, v59, vcc
	v_add_co_u32_e32 v38, vcc, s25, v58
	global_load_dwordx4 v[30:33], v[58:59], off
	s_nop 0
	global_load_dwordx4 v[34:37], v[34:35], off
	v_addc_co_u32_e32 v39, vcc, 0, v59, vcc
	v_add_co_u32_e32 v42, vcc, s26, v58
	v_or_b32_e32 v29, s18, v6
	s_nop 0
	v_addc_co_u32_e32 v43, vcc, 0, v59, vcc
	v_add_co_u32_e32 v46, vcc, s27, v58
	global_load_dwordx4 v[38:41], v[38:39], off
	s_nop 0
	global_load_dwordx4 v[42:45], v[42:43], off
	v_addc_co_u32_e32 v47, vcc, 0, v59, vcc
	v_add_co_u32_e32 v50, vcc, s38, v58
	s_nop 1
	v_addc_co_u32_e32 v51, vcc, 0, v59, vcc
	global_load_dwordx4 v[46:49], v[46:47], off
	s_nop 0
	global_load_dwordx4 v[50:53], v[50:51], off
	v_add_co_u32_e32 v54, vcc, s39, v58
	s_nop 1
	v_addc_co_u32_e32 v55, vcc, 0, v59, vcc
	global_load_dwordx4 v[54:57], v[54:55], off
	v_add_co_u32_e32 v58, vcc, s40, v58
	s_nop 1
	v_addc_co_u32_e32 v59, vcc, 0, v59, vcc
	global_load_dwordx4 v[58:61], v[58:59], off
	s_waitcnt vmcnt(7)
	ds_write2_b32 v11, v30, v31 offset1:1
	ds_write2_b32 v11, v32, v33 offset0:2 offset1:3
	s_waitcnt vmcnt(6)
	ds_write2_b32 v12, v34, v35 offset1:1
	ds_write2_b32 v13, v36, v37 offset1:1
	s_waitcnt vmcnt(5)
	ds_write2_b32 v14, v38, v39 offset1:1
	ds_write2_b32 v15, v40, v41 offset1:1
	s_waitcnt vmcnt(4)
	ds_write2_b32 v16, v42, v43 offset1:1
	ds_write2_b32 v17, v44, v45 offset1:1
	s_waitcnt vmcnt(3)
	ds_write2_b32 v18, v46, v47 offset1:1
	ds_write2_b32 v19, v48, v49 offset1:1
	s_waitcnt vmcnt(2)
	ds_write2_b32 v20, v50, v51 offset1:1
	ds_write2_b32 v21, v52, v53 offset1:1
	s_waitcnt vmcnt(1)
	ds_write2_b32 v22, v54, v55 offset1:1
	ds_write2_b32 v23, v56, v57 offset1:1
	s_waitcnt vmcnt(0)
	ds_write2_b32 v24, v58, v59 offset1:1
	ds_write2_b32 v25, v60, v61 offset1:1
	s_waitcnt lgkmcnt(0)
	ds_read2_b32 v[100:101], v10 offset1:33
	ds_read2_b32 v[102:103], v10 offset0:66 offset1:99
	ds_read2_b32 v[104:105], v10 offset0:132 offset1:165
	ds_read2_b32 v[106:107], v10 offset0:198 offset1:231
	ds_read2_b32 v[108:109], v10 offset0:8 offset1:41
	ds_read2_b32 v[110:111], v10 offset0:74 offset1:107
	ds_read2_b32 v[112:113], v10 offset0:140 offset1:173
	ds_read2_b32 v[114:115], v10 offset0:206 offset1:239
	ds_read2_b32 v[116:117], v10 offset0:16 offset1:49
	ds_read2_b32 v[118:119], v10 offset0:82 offset1:115
	ds_read2_b32 v[120:121], v10 offset0:148 offset1:181
	ds_read2_b32 v[122:123], v10 offset0:214 offset1:247
	ds_read2_b32 v[124:125], v10 offset0:24 offset1:57
	ds_read2_b32 v[126:127], v10 offset0:90 offset1:123
	ds_read2_b32 v[128:129], v10 offset0:156 offset1:189
	ds_read2_b32 v[130:131], v10 offset0:222 offset1:255
	s_waitcnt lgkmcnt(15)
	v_cvt_pk_bf16_f32 v30, v100, v101
	s_waitcnt lgkmcnt(14)
	v_cvt_pk_bf16_f32 v31, v102, v103
	v_lshl_add_u64 v[36:37], s[54:55], 1, v[2:3]
	s_waitcnt lgkmcnt(13)
	v_cvt_pk_bf16_f32 v32, v104, v105
	s_waitcnt lgkmcnt(12)
	v_cvt_pk_bf16_f32 v33, v106, v107
	v_mad_i64_i32 v[38:39], s[54:55], v29, s41, v[36:37]
	global_store_dwordx4 v[38:39], v[30:33], off
	v_or_b32_e32 v29, s18, v7
	v_mad_i64_i32 v[38:39], s[54:55], v29, s41, v[36:37]
	s_waitcnt lgkmcnt(11)
	v_cvt_pk_bf16_f32 v30, v108, v109
	s_waitcnt lgkmcnt(10)
	v_cvt_pk_bf16_f32 v31, v110, v111
	s_waitcnt lgkmcnt(9)
	v_cvt_pk_bf16_f32 v32, v112, v113
	s_waitcnt lgkmcnt(8)
	v_cvt_pk_bf16_f32 v33, v114, v115
	global_store_dwordx4 v[38:39], v[30:33], off
	v_or_b32_e32 v29, s18, v8
	v_mad_i64_i32 v[38:39], s[54:55], v29, s41, v[36:37]
	s_waitcnt lgkmcnt(7)
	v_cvt_pk_bf16_f32 v30, v116, v117
	s_waitcnt lgkmcnt(6)
	v_cvt_pk_bf16_f32 v31, v118, v119
	s_waitcnt lgkmcnt(5)
	v_cvt_pk_bf16_f32 v32, v120, v121
	s_waitcnt lgkmcnt(4)
	v_cvt_pk_bf16_f32 v33, v122, v123
	global_store_dwordx4 v[38:39], v[30:33], off
	v_add_u32_e32 v29, s18, v9
	s_waitcnt lgkmcnt(3)
	v_cvt_pk_bf16_f32 v30, v124, v125
	s_waitcnt lgkmcnt(2)
	v_cvt_pk_bf16_f32 v31, v126, v127
	s_waitcnt lgkmcnt(1)
	v_cvt_pk_bf16_f32 v32, v128, v129
	s_waitcnt lgkmcnt(0)
	v_cvt_pk_bf16_f32 v33, v130, v131
	v_mad_i64_i32 v[34:35], s[18:19], v29, s41, v[36:37]
	global_store_dwordx4 v[34:35], v[30:33], off
	s_waitcnt lgkmcnt(0)
	s_mov_b64 s[18:19], 0
; __device__ __forceinline__ unsigned cvt_pk_bf16(float lo, float hi) { unsigned r; asm volatile("v_cvt_pk_bf16_f32 %0, %1, %2" : "=v"(r) : "v"(lo), "v"(hi)); return r; }
; #define LAS __attribute__((address_space(3)))
; __device__ __forceinline__ void transpose_item(const float* W, int K, int N, bf16_t* WT, const float* kscale, int kind, LAS float* scr, int item, int lane) {
;     const int nblk = N / 32, kb = item / nblk, nb = item % nblk, k0 = 64 * kb, n0 = 32 * nb;
;     {
;         const float* src = W + (size_t)(k0 + (lane >> 3)) * N + n0 + (lane & 7) * 4;
;         f32x4 t[8];
; #pragma unroll
;         for (int i = 0; i < 8; ++i) t[i] = *(const f32x4*)(src + (size_t)(8 * i) * N);
; #pragma unroll
;         for (int i = 0; i < 8; ++i) {
;             const int kk = 8 * i + (lane >> 3);
;             f32x4 v = t[i]; if (kscale) v = v * kscale[k0 + kk];
;             LAS float* d = scr + kk * 33 + (lane & 7) * 4;
;             d[0] = v[0]; d[1] = v[1]; d[2] = v[2]; d[3] = v[3];
;         }
;     }
;     asm volatile("s_waitcnt lgkmcnt(0)" ::: "memory");
;     const int c = lane & 7;
; #pragma unroll
;     for (int j = 0; j < 4; ++j) {
;         const int n = (lane >> 3) + 8 * j; const LAS float* s = scr + (8 * c) * 33 + n;
;         int drow; float sc; map_col(kind, n0 + n, drow, sc);
;         u32x4 ov; ov.x = cvt_pk_bf16(s[0 * 33] * sc, s[1 * 33] * sc); ov.y = cvt_pk_bf16(s[2 * 33] * sc, s[3 * 33] * sc); ov.z = cvt_pk_bf16(s[4 * 33] * sc, s[5 * 33] * sc); ov.w = cvt_pk_bf16(s[6 * 33] * sc, s[7 * 33] * sc);
;         *(u32x4*)(WT + (size_t)drow * K + k0 + 8 * c) = ov;
;     }
;     asm volatile("s_waitcnt lgkmcnt(0)" ::: "memory");
; template <bool DRAIN>
; __device__ __forceinline__ void bg_convert(const float* wg1, const float* wu1, const float* wd1, unsigned char* wsw, unsigned* ctl, int done_word, int G, LAS float* scr, int lane) {
;     ...
;         for (int i = i0; i < i0 + 4; ++i) {
;             const int m = i / BG_ITEMS_PER, it = i - m * BG_ITEMS_PER;
;             if (m == 0) transpose_item(wg1, DM, FFN, (bf16_t*)(wsw + W1_GU), nullptr, MAP_GATE, scr, it, lane);
;             else if (m == 1) transpose_item(wu1, DM, FFN, (bf16_t*)(wsw + W1_GU), nullptr, MAP_UP, scr, it, lane);
;             else transpose_item(wd1, FFN, DM, (bf16_t*)(wsw + W1_DN), nullptr, MAP_ID, scr, it, lane);
.LBB0_920:
	s_andn2_b64 vcc, exec, s[18:19]
	s_cbranch_vccnz .LBB0_922
	s_and_b32 s16, 0xffff, s22
	s_mul_i32 s16, s16, 0xba2f
	s_lshr_b32 s19, s16, 23
	s_mul_i32 s16, s19, 0xb0
	s_sub_i32 s16, s22, s16
	s_lshl_b32 s16, s16, 5
	s_and_b32 s18, s16, 0xffe0
	v_lshl_or_b32 v29, s19, 6, v6
	v_mov_b64_e32 v[30:31], s[6:7]
	v_mad_u64_u32 v[30:31], s[54:55], v29, s42, v[30:31]
	s_lshl_b32 s16, s18, 2
	v_lshl_add_u64 v[30:31], v[30:31], 0, s[16:17]
	v_lshl_add_u64 v[58:59], v[30:31], 0, v[0:1]
	v_add_co_u32_e32 v34, vcc, s43, v58
	v_mov_b32_e32 v29, s18
	s_nop 0
	v_addc_co_u32_e32 v35, vcc, 0, v59, vcc
	v_add_co_u32_e32 v38, vcc, s44, v58
	global_load_dwordx4 v[30:33], v[58:59], off
	s_nop 0
	global_load_dwordx4 v[34:37], v[34:35], off
	v_addc_co_u32_e32 v39, vcc, 0, v59, vcc
	v_add_co_u32_e32 v42, vcc, s45, v58
	s_lshl_b32 s23, s18, 1
	s_nop 0
	v_addc_co_u32_e32 v43, vcc, 0, v59, vcc
	v_add_co_u32_e32 v46, vcc, s46, v58
	global_load_dwordx4 v[38:41], v[38:39], off
	s_nop 0
	global_load_dwordx4 v[42:45], v[42:43], off
	v_addc_co_u32_e32 v47, vcc, 0, v59, vcc
	v_add_co_u32_e32 v50, vcc, s47, v58
	s_lshl_b32 s16, s19, 7
	s_nop 0
	v_addc_co_u32_e32 v51, vcc, 0, v59, vcc
	global_load_dwordx4 v[46:49], v[46:47], off
	s_nop 0
	global_load_dwordx4 v[50:53], v[50:51], off
	v_add_co_u32_e32 v54, vcc, s48, v58
	s_and_b32 s19, s23, 0xff00
	s_nop 0
	v_addc_co_u32_e32 v55, vcc, 0, v59, vcc
	global_load_dwordx4 v[54:57], v[54:55], off
	v_add_co_u32_e32 v58, vcc, s49, v58
	s_nop 1
	v_addc_co_u32_e32 v59, vcc, 0, v59, vcc
	global_load_dwordx4 v[58:61], v[58:59], off
	s_waitcnt vmcnt(7)
	ds_write2_b32 v11, v30, v31 offset1:1
	ds_write2_b32 v11, v32, v33 offset0:2 offset1:3
	s_waitcnt vmcnt(6)
	ds_write2_b32 v12, v34, v35 offset1:1
	ds_write2_b32 v13, v36, v37 offset1:1
	s_waitcnt vmcnt(5)
	ds_write2_b32 v14, v38, v39 offset1:1
	ds_write2_b32 v15, v40, v41 offset1:1
	s_waitcnt vmcnt(4)
	ds_write2_b32 v16, v42, v43 offset1:1
	ds_write2_b32 v17, v44, v45 offset1:1
	s_waitcnt vmcnt(3)
	ds_write2_b32 v18, v46, v47 offset1:1
	ds_write2_b32 v19, v48, v49 offset1:1
	s_waitcnt vmcnt(2)
	ds_write2_b32 v20, v50, v51 offset1:1
	ds_write2_b32 v21, v52, v53 offset1:1
	s_waitcnt vmcnt(1)
	ds_write2_b32 v22, v54, v55 offset1:1
	ds_write2_b32 v23, v56, v57 offset1:1
	s_waitcnt vmcnt(0)
	ds_write2_b32 v24, v58, v59 offset1:1
	ds_write2_b32 v25, v60, v61 offset1:1
	s_waitcnt lgkmcnt(0)
	ds_read2_b32 v[100:101], v10 offset1:33
	ds_read2_b32 v[102:103], v10 offset0:66 offset1:99
	ds_read2_b32 v[104:105], v10 offset0:132 offset1:165
	ds_read2_b32 v[106:107], v10 offset0:198 offset1:231
	ds_read2_b32 v[108:109], v10 offset0:8 offset1:41
	ds_read2_b32 v[110:111], v10 offset0:74 offset1:107
	ds_read2_b32 v[112:113], v10 offset0:140 offset1:173
	ds_read2_b32 v[114:115], v10 offset0:206 offset1:239
	ds_read2_b32 v[116:117], v10 offset0:16 offset1:49
	ds_read2_b32 v[118:119], v10 offset0:82 offset1:115
	ds_read2_b32 v[120:121], v10 offset0:148 offset1:181
	ds_read2_b32 v[122:123], v10 offset0:214 offset1:247
	ds_read2_b32 v[124:125], v10 offset0:24 offset1:57
	ds_read2_b32 v[126:127], v10 offset0:90 offset1:123
	ds_read2_b32 v[128:129], v10 offset0:156 offset1:189
	ds_read2_b32 v[130:131], v10 offset0:222 offset1:255
	s_waitcnt lgkmcnt(15)
	v_cvt_pk_bf16_f32 v30, v100, v101
	v_bitop3_b32 v34, v6, s50, v29 bitop3:0xc8
	s_waitcnt lgkmcnt(14)
	v_cvt_pk_bf16_f32 v31, v102, v103
	v_or_b32_e32 v34, s19, v34
	v_mov_b32_e32 v35, v1
	s_waitcnt lgkmcnt(13)
	v_cvt_pk_bf16_f32 v32, v104, v105
	v_lshl_add_u64 v[38:39], v[4:5], 0, s[16:17]
	v_lshl_or_b32 v34, v34, 12, v26
	s_waitcnt lgkmcnt(12)
	v_cvt_pk_bf16_f32 v33, v106, v107
	v_lshl_add_u64 v[34:35], v[38:39], 0, v[34:35]
	global_store_dwordx4 v[34:35], v[30:33], off
	s_nop 0
	s_waitcnt lgkmcnt(11)
	v_cvt_pk_bf16_f32 v30, v108, v109
	v_bitop3_b32 v36, v7, s51, v29 bitop3:0xc8
	v_or_b32_e32 v36, s19, v36
	s_waitcnt lgkmcnt(10)
	v_cvt_pk_bf16_f32 v31, v110, v111
	v_mov_b32_e32 v37, v1
	v_lshl_or_b32 v36, v36, 12, v26
	s_waitcnt lgkmcnt(9)
	v_cvt_pk_bf16_f32 v32, v112, v113
	s_waitcnt lgkmcnt(8)
	v_cvt_pk_bf16_f32 v33, v114, v115
	v_lshl_add_u64 v[36:37], v[38:39], 0, v[36:37]
	v_bitop3_b32 v29, v8, s51, v29 bitop3:0xc8
	global_store_dwordx4 v[36:37], v[30:33], off
	v_or_b32_e32 v29, s19, v29
	v_mov_b32_e32 v37, v1
	s_waitcnt lgkmcnt(7)
	v_cvt_pk_bf16_f32 v30, v116, v117
	s_waitcnt lgkmcnt(6)
	v_cvt_pk_bf16_f32 v31, v118, v119
	v_lshl_or_b32 v36, v29, 12, v26
	s_waitcnt lgkmcnt(5)
	v_cvt_pk_bf16_f32 v32, v120, v121
	s_waitcnt lgkmcnt(4)
	v_cvt_pk_bf16_f32 v33, v122, v123
	v_lshl_add_u64 v[36:37], v[38:39], 0, v[36:37]
	global_store_dwordx4 v[36:37], v[30:33], off
	v_add_u32_e32 v29, s18, v9
	s_waitcnt lgkmcnt(3)
	v_cvt_pk_bf16_f32 v30, v124, v125
	s_waitcnt lgkmcnt(2)
	v_cvt_pk_bf16_f32 v31, v126, v127
	s_waitcnt lgkmcnt(1)
	v_cvt_pk_bf16_f32 v32, v128, v129
	v_lshlrev_b32_e32 v33, 1, v29
	v_and_b32_e32 v33, 0x1ff00, v33
	v_and_or_b32 v29, v29, s51, v33
	v_mov_b32_e32 v35, v1
	v_lshl_or_b32 v34, v29, 12, v26
	v_lshl_add_u64 v[34:35], v[38:39], 0, v[34:35]
	s_waitcnt lgkmcnt(0)
	v_cvt_pk_bf16_f32 v33, v130, v131
	global_store_dwordx4 v[34:35], v[30:33], off
	s_waitcnt lgkmcnt(0)

; __device__ __forceinline__ unsigned cvt_pk_bf16(float lo, float hi) { unsigned r; asm volatile("v_cvt_pk_bf16_f32 %0, %1, %2" : "=v"(r) : "v"(lo), "v"(hi)); return r; }
; #define LAS __attribute__((address_space(3)))
; __device__ __forceinline__ void transpose_item(const float* W, int K, int N, bf16_t* WT, const float* kscale, int kind, LAS float* scr, int item, int lane) {
;     const int nblk = N / 32, kb = item / nblk, nb = item % nblk, k0 = 64 * kb, n0 = 32 * nb;
;     {
;         const float* src = W + (size_t)(k0 + (lane >> 3)) * N + n0 + (lane & 7) * 4;
;         f32x4 t[8];
; #pragma unroll
;         for (int i = 0; i < 8; ++i) t[i] = *(const f32x4*)(src + (size_t)(8 * i) * N);
; #pragma unroll
;         for (int i = 0; i < 8; ++i) {
;             const int kk = 8 * i + (lane >> 3);
;             f32x4 v = t[i]; if (kscale) v = v * kscale[k0 + kk];
;             LAS float* d = scr + kk * 33 + (lane & 7) * 4;
;             d[0] = v[0]; d[1] = v[1]; d[2] = v[2]; d[3] = v[3];
;         }
;     }
;     asm volatile("s_waitcnt lgkmcnt(0)" ::: "memory");
;     const int c = lane & 7;
; #pragma unroll
;     for (int j = 0; j < 4; ++j) {
;         const int n = (lane >> 3) + 8 * j; const LAS float* s = scr + (8 * c) * 33 + n;
;         int drow; float sc; map_col(kind, n0 + n, drow, sc);
;         u32x4 ov; ov.x = cvt_pk_bf16(s[0 * 33] * sc, s[1 * 33] * sc); ov.y = cvt_pk_bf16(s[2 * 33] * sc, s[3 * 33] * sc); ov.z = cvt_pk_bf16(s[4 * 33] * sc, s[5 * 33] * sc); ov.w = cvt_pk_bf16(s[6 * 33] * sc, s[7 * 33] * sc);
;         *(u32x4*)(WT + (size_t)drow * K + k0 + 8 * c) = ov;
;     }
;     asm volatile("s_waitcnt lgkmcnt(0)" ::: "memory");
; template <bool DRAIN>
; __device__ __forceinline__ void bg_convert(const float* wg1, const float* wu1, const float* wd1, unsigned char* wsw, unsigned* ctl, int done_word, int G, LAS float* scr, int lane) {
;     ...
;         for (int i = i0; i < i0 + 4; ++i) {
;             const int m = i / BG_ITEMS_PER, it = i - m * BG_ITEMS_PER;
;             if (m == 0) transpose_item(wg1, DM, FFN, (bf16_t*)(wsw + W1_GU), nullptr, MAP_GATE, scr, it, lane);
;             else if (m == 1) transpose_item(wu1, DM, FFN, (bf16_t*)(wsw + W1_GU), nullptr, MAP_UP, scr, it, lane);
;             else transpose_item(wd1, FFN, DM, (bf16_t*)(wsw + W1_DN), nullptr, MAP_ID, scr, it, lane);
.LBB0_923:
	s_sext_i32_i16 s16, s22
	s_mulk_i32 s16, 0xba3
	s_lshr_b32 s18, s16, 31
	s_ashr_i32 s16, s16, 19
	s_add_i32 s16, s16, s18
	s_mul_i32 s18, s16, 0xb0
	s_sub_i32 s18, s22, s18
	s_sext_i32_i16 s53, s18
	s_lshl_b32 s22, s16, 6
	s_lshl_b32 s18, s53, 5
	v_or_b32_e32 v29, s22, v6
	v_mov_b64_e32 v[30:31], s[8:9]
	v_mad_i64_i32 v[30:31], s[54:55], v29, s42, v[30:31]
	s_ashr_i32 s19, s18, 31
	v_lshl_add_u64 v[30:31], s[18:19], 2, v[30:31]
	v_lshl_add_u64 v[58:59], v[30:31], 0, v[0:1]
	v_add_co_u32_e32 v34, vcc, s43, v58
	s_lshl_b32 s16, s53, 6
	s_nop 0
	v_addc_co_u32_e32 v35, vcc, 0, v59, vcc
	v_add_co_u32_e32 v38, vcc, s44, v58
	global_load_dwordx4 v[30:33], v[58:59], off
	s_nop 0
	global_load_dwordx4 v[34:37], v[34:35], off
	v_addc_co_u32_e32 v39, vcc, 0, v59, vcc
	v_add_co_u32_e32 v42, vcc, s45, v58
	v_bitop3_b32 v29, s18, v27, v6 bitop3:0xc8
	s_nop 0
	v_addc_co_u32_e32 v43, vcc, 0, v59, vcc
	v_add_co_u32_e32 v46, vcc, s46, v58
	global_load_dwordx4 v[38:41], v[38:39], off
	s_nop 0
	global_load_dwordx4 v[42:45], v[42:43], off
	v_addc_co_u32_e32 v47, vcc, 0, v59, vcc
	v_add_co_u32_e32 v50, vcc, s47, v58
	s_and_b32 s16, s16, 0xffffff00
	s_nop 0
	v_addc_co_u32_e32 v51, vcc, 0, v59, vcc
	global_load_dwordx4 v[46:49], v[46:47], off
	s_nop 0
	global_load_dwordx4 v[50:53], v[50:51], off
	v_add_co_u32_e32 v54, vcc, s48, v58
	s_ashr_i32 s23, s22, 31
	s_nop 0
	v_addc_co_u32_e32 v55, vcc, 0, v59, vcc
	global_load_dwordx4 v[54:57], v[54:55], off
	v_add_co_u32_e32 v58, vcc, s49, v58
	s_nop 1
	v_addc_co_u32_e32 v59, vcc, 0, v59, vcc
	global_load_dwordx4 v[58:61], v[58:59], off
	s_waitcnt vmcnt(7)
	ds_write2_b32 v11, v30, v31 offset1:1
	ds_write2_b32 v11, v32, v33 offset0:2 offset1:3
	s_waitcnt vmcnt(6)
	ds_write2_b32 v12, v34, v35 offset1:1
	ds_write2_b32 v13, v36, v37 offset1:1
	s_waitcnt vmcnt(5)
	ds_write2_b32 v14, v38, v39 offset1:1
	ds_write2_b32 v15, v40, v41 offset1:1
	s_waitcnt vmcnt(4)
	ds_write2_b32 v16, v42, v43 offset1:1
	ds_write2_b32 v17, v44, v45 offset1:1
	s_waitcnt vmcnt(3)
	ds_write2_b32 v18, v46, v47 offset1:1
	ds_write2_b32 v19, v48, v49 offset1:1
	s_waitcnt vmcnt(2)
	ds_write2_b32 v20, v50, v51 offset1:1
	ds_write2_b32 v21, v52, v53 offset1:1
	s_waitcnt vmcnt(1)
	ds_write2_b32 v22, v54, v55 offset1:1
	ds_write2_b32 v23, v56, v57 offset1:1
	s_waitcnt vmcnt(0)
	ds_write2_b32 v24, v58, v59 offset1:1
	ds_write2_b32 v25, v60, v61 offset1:1
	s_waitcnt lgkmcnt(0)
	v_or_b32_e32 v38, s16, v29
	ds_read2_b32 v[100:101], v10 offset1:33
	ds_read2_b32 v[102:103], v10 offset0:66 offset1:99
	ds_read2_b32 v[104:105], v10 offset0:132 offset1:165
	ds_read2_b32 v[106:107], v10 offset0:198 offset1:231
	ds_read2_b32 v[108:109], v10 offset0:8 offset1:41
	ds_read2_b32 v[110:111], v10 offset0:74 offset1:107
	ds_read2_b32 v[112:113], v10 offset0:140 offset1:173
	ds_read2_b32 v[114:115], v10 offset0:206 offset1:239
	ds_read2_b32 v[116:117], v10 offset0:16 offset1:49
	ds_read2_b32 v[118:119], v10 offset0:82 offset1:115
	ds_read2_b32 v[120:121], v10 offset0:148 offset1:181
	ds_read2_b32 v[122:123], v10 offset0:214 offset1:247
	ds_read2_b32 v[124:125], v10 offset0:24 offset1:57
	ds_read2_b32 v[126:127], v10 offset0:90 offset1:123
	ds_read2_b32 v[128:129], v10 offset0:156 offset1:189
	ds_read2_b32 v[130:131], v10 offset0:222 offset1:255
	v_ashrrev_i32_e32 v39, 31, v38
	s_waitcnt lgkmcnt(15)
	v_cvt_pk_bf16_f32 v30, v100, v101
	v_lshl_add_u64 v[34:35], s[22:23], 1, v[4:5]
	v_lshlrev_b64 v[38:39], 12, v[38:39]
	s_waitcnt lgkmcnt(14)
	v_cvt_pk_bf16_f32 v31, v102, v103
	v_lshl_add_u64 v[38:39], v[34:35], 0, v[38:39]
	v_bitop3_b32 v29, s18, v28, v7 bitop3:0xc8
	s_waitcnt lgkmcnt(13)
	v_cvt_pk_bf16_f32 v32, v104, v105
	s_waitcnt lgkmcnt(12)
	v_cvt_pk_bf16_f32 v33, v106, v107
	global_store_dwordx4 v[38:39], v[30:33], off
	v_or_b32_e32 v38, s16, v29
	v_ashrrev_i32_e32 v39, 31, v38
	s_waitcnt lgkmcnt(11)
	v_cvt_pk_bf16_f32 v30, v108, v109
	v_lshlrev_b64 v[38:39], 12, v[38:39]
	s_waitcnt lgkmcnt(10)
	v_cvt_pk_bf16_f32 v31, v110, v111
	v_lshl_add_u64 v[38:39], v[34:35], 0, v[38:39]
	v_bitop3_b32 v29, s18, v28, v8 bitop3:0xc8
	s_waitcnt lgkmcnt(9)
	v_cvt_pk_bf16_f32 v32, v112, v113
	s_waitcnt lgkmcnt(8)
	v_cvt_pk_bf16_f32 v33, v114, v115
	global_store_dwordx4 v[38:39], v[30:33], off
	v_or_b32_e32 v38, s16, v29
	v_ashrrev_i32_e32 v39, 31, v38
	s_waitcnt lgkmcnt(7)
	v_cvt_pk_bf16_f32 v30, v116, v117
	v_lshlrev_b64 v[38:39], 12, v[38:39]
	s_waitcnt lgkmcnt(6)
	v_cvt_pk_bf16_f32 v31, v118, v119
	v_lshl_add_u64 v[38:39], v[34:35], 0, v[38:39]
	v_add_u32_e32 v29, s18, v9
	s_waitcnt lgkmcnt(5)
	v_cvt_pk_bf16_f32 v32, v120, v121
	s_waitcnt lgkmcnt(4)
	v_cvt_pk_bf16_f32 v33, v122, v123
	global_store_dwordx4 v[38:39], v[30:33], off
	v_lshlrev_b32_e32 v38, 1, v29
	v_and_b32_e32 v29, 0x7f, v29
	v_and_or_b32 v38, v38, s52, v29
	v_ashrrev_i32_e32 v39, 31, v38
	s_waitcnt lgkmcnt(3)
	v_cvt_pk_bf16_f32 v30, v124, v125
	v_lshlrev_b64 v[38:39], 12, v[38:39]
	s_waitcnt lgkmcnt(2)
	v_cvt_pk_bf16_f32 v31, v126, v127
	v_lshl_add_u64 v[34:35], v[34:35], 0, v[38:39]
	s_waitcnt lgkmcnt(1)
	v_cvt_pk_bf16_f32 v32, v128, v129
	s_waitcnt lgkmcnt(0)
	v_cvt_pk_bf16_f32 v33, v130, v131
	global_store_dwordx4 v[34:35], v[30:33], off
	s_waitcnt lgkmcnt(0)
	s_branch .LBB0_915

; __device__ __forceinline__ unsigned cvt_pk_bf16(float lo, float hi) { unsigned r; asm volatile("v_cvt_pk_bf16_f32 %0, %1, %2" : "=v"(r) : "v"(lo), "v"(hi)); return r; }
; #define LAS __attribute__((address_space(3)))
; __device__ __forceinline__ void transpose_item(const float* W, int K, int N, bf16_t* WT, const float* kscale, int kind, LAS float* scr, int item, int lane) {
;     const int nblk = N / 32, kb = item / nblk, nb = item % nblk, k0 = 64 * kb, n0 = 32 * nb;
;     {
;         const float* src = W + (size_t)(k0 + (lane >> 3)) * N + n0 + (lane & 7) * 4;
;         f32x4 t[8];
; #pragma unroll
;         for (int i = 0; i < 8; ++i) t[i] = *(const f32x4*)(src + (size_t)(8 * i) * N);
; #pragma unroll
;         for (int i = 0; i < 8; ++i) {
;             const int kk = 8 * i + (lane >> 3);
;             f32x4 v = t[i]; if (kscale) v = v * kscale[k0 + kk];
;             LAS float* d = scr + kk * 33 + (lane & 7) * 4;
;             d[0] = v[0]; d[1] = v[1]; d[2] = v[2]; d[3] = v[3];
;         }
;     }
;     asm volatile("s_waitcnt lgkmcnt(0)" ::: "memory");
;     const int c = lane & 7;
; #pragma unroll
;     for (int j = 0; j < 4; ++j) {
;         const int n = (lane >> 3) + 8 * j; const LAS float* s = scr + (8 * c) * 33 + n;
;         int drow; float sc; map_col(kind, n0 + n, drow, sc);
;         u32x4 ov; ov.x = cvt_pk_bf16(s[0 * 33] * sc, s[1 * 33] * sc); ov.y = cvt_pk_bf16(s[2 * 33] * sc, s[3 * 33] * sc); ov.z = cvt_pk_bf16(s[4 * 33] * sc, s[5 * 33] * sc); ov.w = cvt_pk_bf16(s[6 * 33] * sc, s[7 * 33] * sc);
;         *(u32x4*)(WT + (size_t)drow * K + k0 + 8 * c) = ov;
;     }
;     asm volatile("s_waitcnt lgkmcnt(0)" ::: "memory");
; template <bool DRAIN>
; __device__ __forceinline__ void bg_convert(const float* wg1, const float* wu1, const float* wd1, unsigned char* wsw, unsigned* ctl, int done_word, int G, LAS float* scr, int lane) {
;     ...
;         for (int i = i0; i < i0 + 4; ++i) {
;             const int m = i / BG_ITEMS_PER, it = i - m * BG_ITEMS_PER;
;             if (m == 0) transpose_item(wg1, DM, FFN, (bf16_t*)(wsw + W1_GU), nullptr, MAP_GATE, scr, it, lane);
;             else if (m == 1) transpose_item(wu1, DM, FFN, (bf16_t*)(wsw + W1_GU), nullptr, MAP_UP, scr, it, lane);
;             else transpose_item(wd1, FFN, DM, (bf16_t*)(wsw + W1_DN), nullptr, MAP_ID, scr, it, lane);
.LBB0_1172:
	s_add_i32 s12, s16, 0xffffea00
	s_cmpk_gt_u32 s12, 0x15ff
	s_cbranch_scc0 .LBB0_1174
	s_sext_i32_i16 s12, s18
	s_bfe_u32 s12, s12, 0x60019
	s_add_i32 s12, s18, s12
	s_sext_i32_i16 s14, s12
	s_and_b32 s12, s12, 0xffc0
	s_and_b32 s50, s14, 0xffffffc0
	s_sub_i32 s12, s18, s12
	v_or_b32_e32 v26, s50, v6
	s_sext_i32_i16 s12, s12
	v_ashrrev_i32_e32 v27, 31, v26
	s_lshl_b32 s14, s12, 5
	v_lshlrev_b64 v[26:27], 13, v[26:27]
	v_lshl_add_u64 v[26:27], s[10:11], 0, v[26:27]
	s_ashr_i32 s15, s14, 31
	v_lshl_add_u64 v[26:27], s[14:15], 2, v[26:27]
	v_lshl_add_u64 v[54:55], v[26:27], 0, v[0:1]
	v_add_co_u32_e32 v30, vcc, s20, v54
	s_ashr_i32 s51, s50, 31
	s_nop 0
	v_addc_co_u32_e32 v31, vcc, 0, v55, vcc
	v_add_co_u32_e32 v34, vcc, s21, v54
	global_load_dwordx4 v[26:29], v[54:55], off
	s_nop 0
	global_load_dwordx4 v[30:33], v[30:31], off
	v_addc_co_u32_e32 v35, vcc, 0, v55, vcc
	v_add_co_u32_e32 v38, vcc, s22, v54
	s_nop 1
	v_addc_co_u32_e32 v39, vcc, 0, v55, vcc
	v_add_co_u32_e32 v42, vcc, s23, v54
	global_load_dwordx4 v[34:37], v[34:35], off
	s_nop 0
	global_load_dwordx4 v[38:41], v[38:39], off
	v_addc_co_u32_e32 v43, vcc, 0, v55, vcc
	v_add_co_u32_e32 v46, vcc, s24, v54
	s_nop 1
	v_addc_co_u32_e32 v47, vcc, 0, v55, vcc
	global_load_dwordx4 v[42:45], v[42:43], off
	s_nop 0
	global_load_dwordx4 v[46:49], v[46:47], off
	v_add_co_u32_e32 v50, vcc, s25, v54
	s_nop 1
	v_addc_co_u32_e32 v51, vcc, 0, v55, vcc
	global_load_dwordx4 v[50:53], v[50:51], off
	v_add_co_u32_e32 v54, vcc, s26, v54
	s_nop 1
	v_addc_co_u32_e32 v55, vcc, 0, v55, vcc
	global_load_dwordx4 v[54:57], v[54:55], off
	s_waitcnt vmcnt(7)
	ds_write2_b32 v11, v26, v27 offset1:1
	ds_write2_b32 v11, v28, v29 offset0:2 offset1:3
	s_waitcnt vmcnt(6)
	ds_write2_b32 v12, v30, v31 offset1:1
	ds_write2_b32 v13, v32, v33 offset1:1
	s_waitcnt vmcnt(5)
	ds_write2_b32 v14, v34, v35 offset1:1
	ds_write2_b32 v15, v36, v37 offset1:1
	s_waitcnt vmcnt(4)
	ds_write2_b32 v16, v38, v39 offset1:1
	ds_write2_b32 v17, v40, v41 offset1:1
	s_waitcnt vmcnt(3)
	ds_write2_b32 v18, v42, v43 offset1:1
	ds_write2_b32 v19, v44, v45 offset1:1
	s_waitcnt vmcnt(2)
	ds_write2_b32 v20, v46, v47 offset1:1
	ds_write2_b32 v21, v48, v49 offset1:1
	s_waitcnt vmcnt(1)
	ds_write2_b32 v22, v50, v51 offset1:1
	ds_write2_b32 v23, v52, v53 offset1:1
	s_waitcnt vmcnt(0)
	ds_write2_b32 v24, v54, v55 offset1:1
	ds_write2_b32 v25, v56, v57 offset1:1
	s_waitcnt lgkmcnt(0)
	v_or_b32_e32 v34, s14, v6
	ds_read2_b32 v[100:101], v10 offset1:33
	ds_read2_b32 v[102:103], v10 offset0:66 offset1:99
	ds_read2_b32 v[104:105], v10 offset0:132 offset1:165
	ds_read2_b32 v[106:107], v10 offset0:198 offset1:231
	ds_read2_b32 v[108:109], v10 offset0:8 offset1:41
	ds_read2_b32 v[110:111], v10 offset0:74 offset1:107
	ds_read2_b32 v[112:113], v10 offset0:140 offset1:173
	ds_read2_b32 v[114:115], v10 offset0:206 offset1:239
	ds_read2_b32 v[116:117], v10 offset0:16 offset1:49
	ds_read2_b32 v[118:119], v10 offset0:82 offset1:115
	ds_read2_b32 v[120:121], v10 offset0:148 offset1:181
	ds_read2_b32 v[122:123], v10 offset0:214 offset1:247
	ds_read2_b32 v[124:125], v10 offset0:24 offset1:57
	ds_read2_b32 v[126:127], v10 offset0:90 offset1:123
	ds_read2_b32 v[128:129], v10 offset0:156 offset1:189
	ds_read2_b32 v[130:131], v10 offset0:222 offset1:255
	v_mul_i32_i24_e32 v34, 0x2c00, v34
	s_waitcnt lgkmcnt(15)
	v_cvt_pk_bf16_f32 v26, v100, v101
	v_lshl_add_u64 v[32:33], s[50:51], 1, v[2:3]
	v_ashrrev_i32_e32 v35, 31, v34
	s_waitcnt lgkmcnt(14)
	v_cvt_pk_bf16_f32 v27, v102, v103
	v_lshl_add_u64 v[34:35], v[32:33], 0, v[34:35]
	s_waitcnt lgkmcnt(13)
	v_cvt_pk_bf16_f32 v28, v104, v105
	s_waitcnt lgkmcnt(12)
	v_cvt_pk_bf16_f32 v29, v106, v107
	global_store_dwordx4 v[34:35], v[26:29], off
	v_or_b32_e32 v34, s14, v7
	v_mul_i32_i24_e32 v34, 0x2c00, v34
	s_waitcnt lgkmcnt(11)
	v_cvt_pk_bf16_f32 v26, v108, v109
	v_ashrrev_i32_e32 v35, 31, v34
	s_waitcnt lgkmcnt(10)
	v_cvt_pk_bf16_f32 v27, v110, v111
	v_lshl_add_u64 v[34:35], v[32:33], 0, v[34:35]
	s_waitcnt lgkmcnt(9)
	v_cvt_pk_bf16_f32 v28, v112, v113
	s_waitcnt lgkmcnt(8)
	v_cvt_pk_bf16_f32 v29, v114, v115
	global_store_dwordx4 v[34:35], v[26:29], off
	v_or_b32_e32 v34, s14, v8
	s_waitcnt lgkmcnt(7)
	v_cvt_pk_bf16_f32 v26, v116, v117
	v_mul_i32_i24_e32 v34, 0x2c00, v34
	s_waitcnt lgkmcnt(6)
	v_cvt_pk_bf16_f32 v27, v118, v119
	v_ashrrev_i32_e32 v35, 31, v34
	s_waitcnt lgkmcnt(5)
	v_cvt_pk_bf16_f32 v28, v120, v121
	s_waitcnt lgkmcnt(4)
	v_cvt_pk_bf16_f32 v29, v122, v123
	v_lshl_add_u64 v[34:35], v[32:33], 0, v[34:35]
	global_store_dwordx4 v[34:35], v[26:29], off
	s_nop 0
	s_waitcnt lgkmcnt(3)
	v_cvt_pk_bf16_f32 v26, v124, v125
	s_waitcnt lgkmcnt(2)
	v_cvt_pk_bf16_f32 v27, v126, v127
	s_waitcnt lgkmcnt(1)
	v_cvt_pk_bf16_f32 v28, v128, v129
	v_or_b32_e32 v29, s14, v9
	v_mul_i32_i24_e32 v34, 0x2c00, v29
	v_ashrrev_i32_e32 v35, 31, v34
	s_waitcnt lgkmcnt(0)
	v_cvt_pk_bf16_f32 v29, v130, v131
	v_lshl_add_u64 v[30:31], v[32:33], 0, v[34:35]
	global_store_dwordx4 v[30:31], v[26:29], off
	s_waitcnt lgkmcnt(0)
	s_mov_b64 s[14:15], 0
; __device__ __forceinline__ unsigned cvt_pk_bf16(float lo, float hi) { unsigned r; asm volatile("v_cvt_pk_bf16_f32 %0, %1, %2" : "=v"(r) : "v"(lo), "v"(hi)); return r; }
; #define LAS __attribute__((address_space(3)))
; __device__ __forceinline__ void transpose_item(const float* W, int K, int N, bf16_t* WT, const float* kscale, int kind, LAS float* scr, int item, int lane) {
;     const int nblk = N / 32, kb = item / nblk, nb = item % nblk, k0 = 64 * kb, n0 = 32 * nb;
;     {
;         const float* src = W + (size_t)(k0 + (lane >> 3)) * N + n0 + (lane & 7) * 4;
;         f32x4 t[8];
; #pragma unroll
;         for (int i = 0; i < 8; ++i) t[i] = *(const f32x4*)(src + (size_t)(8 * i) * N);
; #pragma unroll
;         for (int i = 0; i < 8; ++i) {
;             const int kk = 8 * i + (lane >> 3);
;             f32x4 v = t[i]; if (kscale) v = v * kscale[k0 + kk];
;             LAS float* d = scr + kk * 33 + (lane & 7) * 4;
;             d[0] = v[0]; d[1] = v[1]; d[2] = v[2]; d[3] = v[3];
;         }
;     }
;     asm volatile("s_waitcnt lgkmcnt(0)" ::: "memory");
;     const int c = lane & 7;
; #pragma unroll
;     for (int j = 0; j < 4; ++j) {
;         const int n = (lane >> 3) + 8 * j; const LAS float* s = scr + (8 * c) * 33 + n;
;         int drow; float sc; map_col(kind, n0 + n, drow, sc);
;         u32x4 ov; ov.x = cvt_pk_bf16(s[0 * 33] * sc, s[1 * 33] * sc); ov.y = cvt_pk_bf16(s[2 * 33] * sc, s[3 * 33] * sc); ov.z = cvt_pk_bf16(s[4 * 33] * sc, s[5 * 33] * sc); ov.w = cvt_pk_bf16(s[6 * 33] * sc, s[7 * 33] * sc);
;         *(u32x4*)(WT + (size_t)drow * K + k0 + 8 * c) = ov;
;     }
;     asm volatile("s_waitcnt lgkmcnt(0)" ::: "memory");
; template <bool DRAIN>
; __device__ __forceinline__ void bg_convert(const float* wg1, const float* wu1, const float* wd1, unsigned char* wsw, unsigned* ctl, int done_word, int G, LAS float* scr, int lane) {
;     ...
;         for (int i = i0; i < i0 + 4; ++i) {
;             const int m = i / BG_ITEMS_PER, it = i - m * BG_ITEMS_PER;
;             if (m == 0) transpose_item(wg1, DM, FFN, (bf16_t*)(wsw + W1_GU), nullptr, MAP_GATE, scr, it, lane);
;             else if (m == 1) transpose_item(wu1, DM, FFN, (bf16_t*)(wsw + W1_GU), nullptr, MAP_UP, scr, it, lane);
;             else transpose_item(wd1, FFN, DM, (bf16_t*)(wsw + W1_DN), nullptr, MAP_ID, scr, it, lane);
.LBB0_1174:
	s_andn2_b64 vcc, exec, s[14:15]
	s_cbranch_vccnz .LBB0_1176
	s_and_b32 s12, 0xffff, s18
	s_mul_i32 s12, s12, 0xba2f
	s_lshr_b32 s14, s12, 23
	s_mul_i32 s12, s14, 0xb0
	s_sub_i32 s15, s18, s12
	s_lshl_b32 s19, s15, 5
	v_lshl_or_b32 v26, s14, 6, v6
	s_and_b32 s12, s19, 0xffe0
	v_mul_u32_u24_e32 v26, 0x5800, v26
	v_mov_b32_e32 v27, v1
	v_lshl_add_u64 v[26:27], s[6:7], 0, v[26:27]
	s_lshl_b32 s12, s12, 2
	v_lshl_add_u64 v[26:27], v[26:27], 0, s[12:13]
	v_lshl_add_u64 v[54:55], v[26:27], 0, v[0:1]
	v_add_co_u32_e32 v30, vcc, s27, v54
	s_lshl_b32 s12, s15, 6
	s_nop 0
	v_addc_co_u32_e32 v31, vcc, 0, v55, vcc
	v_add_co_u32_e32 v34, vcc, s42, v54
	global_load_dwordx4 v[26:29], v[54:55], off
	s_nop 0
	global_load_dwordx4 v[30:33], v[30:31], off
	v_addc_co_u32_e32 v35, vcc, 0, v55, vcc
	v_add_co_u32_e32 v38, vcc, s43, v54
	s_and_b32 s12, s12, 0x3f00
	s_nop 0
	v_addc_co_u32_e32 v39, vcc, 0, v55, vcc
	v_add_co_u32_e32 v42, vcc, s44, v54
	global_load_dwordx4 v[34:37], v[34:35], off
	s_nop 0
	global_load_dwordx4 v[38:41], v[38:39], off
	v_addc_co_u32_e32 v43, vcc, 0, v55, vcc
	v_add_co_u32_e32 v46, vcc, s45, v54
	s_and_b32 s15, s19, 0x60
	s_nop 0
	v_addc_co_u32_e32 v47, vcc, 0, v55, vcc
	global_load_dwordx4 v[42:45], v[42:43], off
	s_nop 0
	global_load_dwordx4 v[46:49], v[46:47], off
	v_add_co_u32_e32 v50, vcc, s46, v54
	s_or_b32 s15, s12, s15
	s_nop 0
	v_addc_co_u32_e32 v51, vcc, 0, v55, vcc
	global_load_dwordx4 v[50:53], v[50:51], off
	v_add_co_u32_e32 v54, vcc, s47, v54
	s_lshl_b32 s12, s14, 7
	s_nop 0
	v_addc_co_u32_e32 v55, vcc, 0, v55, vcc
	global_load_dwordx4 v[54:57], v[54:55], off
	s_waitcnt vmcnt(7)
	ds_write2_b32 v11, v26, v27 offset1:1
	ds_write2_b32 v11, v28, v29 offset0:2 offset1:3
	s_waitcnt vmcnt(6)
	ds_write2_b32 v12, v30, v31 offset1:1
	ds_write2_b32 v13, v32, v33 offset1:1
	s_waitcnt vmcnt(5)
	ds_write2_b32 v14, v34, v35 offset1:1
	ds_write2_b32 v15, v36, v37 offset1:1
	s_waitcnt vmcnt(4)
	ds_write2_b32 v16, v38, v39 offset1:1
	ds_write2_b32 v17, v40, v41 offset1:1
	s_waitcnt vmcnt(3)
	ds_write2_b32 v18, v42, v43 offset1:1
	ds_write2_b32 v19, v44, v45 offset1:1
	s_waitcnt vmcnt(2)
	ds_write2_b32 v20, v46, v47 offset1:1
	ds_write2_b32 v21, v48, v49 offset1:1
	s_waitcnt vmcnt(1)
	ds_write2_b32 v22, v50, v51 offset1:1
	ds_write2_b32 v23, v52, v53 offset1:1
	s_waitcnt vmcnt(0)
	ds_write2_b32 v24, v54, v55 offset1:1
	ds_write2_b32 v25, v56, v57 offset1:1
	s_waitcnt lgkmcnt(0)
	ds_read2_b32 v[100:101], v10 offset1:33
	ds_read2_b32 v[102:103], v10 offset0:66 offset1:99
	ds_read2_b32 v[104:105], v10 offset0:132 offset1:165
	ds_read2_b32 v[106:107], v10 offset0:198 offset1:231
	ds_read2_b32 v[108:109], v10 offset0:8 offset1:41
	ds_read2_b32 v[110:111], v10 offset0:74 offset1:107
	ds_read2_b32 v[112:113], v10 offset0:140 offset1:173
	ds_read2_b32 v[114:115], v10 offset0:206 offset1:239
	ds_read2_b32 v[116:117], v10 offset0:16 offset1:49
	ds_read2_b32 v[118:119], v10 offset0:82 offset1:115
	ds_read2_b32 v[120:121], v10 offset0:148 offset1:181
	ds_read2_b32 v[122:123], v10 offset0:214 offset1:247
	ds_read2_b32 v[124:125], v10 offset0:24 offset1:57
	ds_read2_b32 v[126:127], v10 offset0:90 offset1:123
	ds_read2_b32 v[128:129], v10 offset0:156 offset1:189
	ds_read2_b32 v[130:131], v10 offset0:222 offset1:255
	s_waitcnt lgkmcnt(15)
	v_cvt_pk_bf16_f32 v26, v100, v101
	s_waitcnt lgkmcnt(14)
	v_cvt_pk_bf16_f32 v27, v102, v103
	s_waitcnt lgkmcnt(13)
	v_cvt_pk_bf16_f32 v28, v104, v105
	v_or_b32_e32 v29, s15, v6
	v_mov_b32_e32 v31, v1
	v_lshl_add_u64 v[34:35], v[4:5], 0, s[12:13]
	v_lshlrev_b32_e32 v30, 12, v29
	v_lshl_add_u64 v[30:31], v[34:35], 0, v[30:31]
	v_add_co_u32_e32 v30, vcc, s48, v30
	s_waitcnt lgkmcnt(12)
	v_cvt_pk_bf16_f32 v29, v106, v107
	v_addc_co_u32_e32 v31, vcc, 0, v31, vcc
	global_store_dwordx4 v[30:31], v[26:29], off
	s_nop 0
	s_waitcnt lgkmcnt(11)
	v_cvt_pk_bf16_f32 v26, v108, v109
	s_waitcnt lgkmcnt(10)
	v_cvt_pk_bf16_f32 v27, v110, v111
	s_waitcnt lgkmcnt(9)
	v_cvt_pk_bf16_f32 v28, v112, v113
	v_or_b32_e32 v29, s15, v7
	v_mov_b32_e32 v33, v1
	v_lshlrev_b32_e32 v32, 12, v29
	v_lshl_add_u64 v[32:33], v[34:35], 0, v[32:33]
	v_add_co_u32_e32 v32, vcc, s48, v32
	s_waitcnt lgkmcnt(8)
	v_cvt_pk_bf16_f32 v29, v114, v115
	v_addc_co_u32_e32 v33, vcc, 0, v33, vcc
	global_store_dwordx4 v[32:33], v[26:29], off
	v_mov_b32_e32 v33, v1
	s_waitcnt lgkmcnt(7)
	v_cvt_pk_bf16_f32 v26, v116, v117
	s_waitcnt lgkmcnt(6)
	v_cvt_pk_bf16_f32 v27, v118, v119
	s_waitcnt lgkmcnt(5)
	v_cvt_pk_bf16_f32 v28, v120, v121
	v_or_b32_e32 v29, s15, v8
	v_lshlrev_b32_e32 v32, 12, v29
	v_lshl_add_u64 v[32:33], v[34:35], 0, v[32:33]
	v_add_co_u32_e32 v32, vcc, s48, v32
	s_waitcnt lgkmcnt(4)
	v_cvt_pk_bf16_f32 v29, v122, v123
	v_addc_co_u32_e32 v33, vcc, 0, v33, vcc
	global_store_dwordx4 v[32:33], v[26:29], off
	s_nop 0
	s_waitcnt lgkmcnt(3)
	v_cvt_pk_bf16_f32 v26, v124, v125
	v_or_b32_e32 v30, s15, v9
	v_mov_b32_e32 v31, v1
	v_lshlrev_b32_e32 v30, 12, v30
	v_lshl_add_u64 v[30:31], v[34:35], 0, v[30:31]
	v_add_co_u32_e32 v30, vcc, 0x80000, v30
	s_waitcnt lgkmcnt(2)
	v_cvt_pk_bf16_f32 v27, v126, v127
	v_addc_co_u32_e32 v31, vcc, 0, v31, vcc
	s_waitcnt lgkmcnt(1)
	v_cvt_pk_bf16_f32 v28, v128, v129
	s_waitcnt lgkmcnt(0)
	v_cvt_pk_bf16_f32 v29, v130, v131
	global_store_dwordx4 v[30:31], v[26:29], off
	s_waitcnt lgkmcnt(0)

; __device__ __forceinline__ unsigned cvt_pk_bf16(float lo, float hi) { unsigned r; asm volatile("v_cvt_pk_bf16_f32 %0, %1, %2" : "=v"(r) : "v"(lo), "v"(hi)); return r; }
; #define LAS __attribute__((address_space(3)))
; __device__ __forceinline__ void transpose_item(const float* W, int K, int N, bf16_t* WT, const float* kscale, int kind, LAS float* scr, int item, int lane) {
;     const int nblk = N / 32, kb = item / nblk, nb = item % nblk, k0 = 64 * kb, n0 = 32 * nb;
;     {
;         const float* src = W + (size_t)(k0 + (lane >> 3)) * N + n0 + (lane & 7) * 4;
;         f32x4 t[8];
; #pragma unroll
;         for (int i = 0; i < 8; ++i) t[i] = *(const f32x4*)(src + (size_t)(8 * i) * N);
; #pragma unroll
;         for (int i = 0; i < 8; ++i) {
;             const int kk = 8 * i + (lane >> 3);
;             f32x4 v = t[i]; if (kscale) v = v * kscale[k0 + kk];
;             LAS float* d = scr + kk * 33 + (lane & 7) * 4;
;             d[0] = v[0]; d[1] = v[1]; d[2] = v[2]; d[3] = v[3];
;         }
;     }
;     asm volatile("s_waitcnt lgkmcnt(0)" ::: "memory");
;     const int c = lane & 7;
; #pragma unroll
;     for (int j = 0; j < 4; ++j) {
;         const int n = (lane >> 3) + 8 * j; const LAS float* s = scr + (8 * c) * 33 + n;
;         int drow; float sc; map_col(kind, n0 + n, drow, sc);
;         u32x4 ov; ov.x = cvt_pk_bf16(s[0 * 33] * sc, s[1 * 33] * sc); ov.y = cvt_pk_bf16(s[2 * 33] * sc, s[3 * 33] * sc); ov.z = cvt_pk_bf16(s[4 * 33] * sc, s[5 * 33] * sc); ov.w = cvt_pk_bf16(s[6 * 33] * sc, s[7 * 33] * sc);
;         *(u32x4*)(WT + (size_t)drow * K + k0 + 8 * c) = ov;
;     }
;     asm volatile("s_waitcnt lgkmcnt(0)" ::: "memory");
; template <bool DRAIN>
; __device__ __forceinline__ void bg_convert(const float* wg1, const float* wu1, const float* wd1, unsigned char* wsw, unsigned* ctl, int done_word, int G, LAS float* scr, int lane) {
;     ...
;         for (int i = i0; i < i0 + 4; ++i) {
;             const int m = i / BG_ITEMS_PER, it = i - m * BG_ITEMS_PER;
;             if (m == 0) transpose_item(wg1, DM, FFN, (bf16_t*)(wsw + W1_GU), nullptr, MAP_GATE, scr, it, lane);
;             else if (m == 1) transpose_item(wu1, DM, FFN, (bf16_t*)(wsw + W1_GU), nullptr, MAP_UP, scr, it, lane);
;             else transpose_item(wd1, FFN, DM, (bf16_t*)(wsw + W1_DN), nullptr, MAP_ID, scr, it, lane);
.LBB0_1177:
	s_sext_i32_i16 s12, s18
	s_mulk_i32 s12, 0xba3
	s_lshr_b32 s14, s12, 31
	s_ashr_i32 s12, s12, 19
	s_add_i32 s12, s12, s14
	s_mul_i32 s14, s12, 0xb0
	s_sub_i32 s14, s18, s14
	s_sext_i32_i16 s49, s14
	s_lshl_b32 s14, s12, 6
	v_or_b32_e32 v26, s14, v6
	v_mul_i32_i24_e32 v26, 0x5800, v26
	s_lshl_b32 s18, s49, 5
	v_ashrrev_i32_e32 v27, 31, v26
	v_lshl_add_u64 v[26:27], s[8:9], 0, v[26:27]
	s_ashr_i32 s19, s18, 31
	v_lshl_add_u64 v[26:27], s[18:19], 2, v[26:27]
	v_lshl_add_u64 v[54:55], v[26:27], 0, v[0:1]
	v_add_co_u32_e32 v30, vcc, s27, v54
	s_ashr_i32 s15, s14, 31
	s_nop 0
	v_addc_co_u32_e32 v31, vcc, 0, v55, vcc
	v_add_co_u32_e32 v34, vcc, s42, v54
	global_load_dwordx4 v[26:29], v[54:55], off
	s_nop 0
	global_load_dwordx4 v[30:33], v[30:31], off
	v_addc_co_u32_e32 v35, vcc, 0, v55, vcc
	v_add_co_u32_e32 v38, vcc, s43, v54
	s_lshl_b32 s12, s49, 6
	s_nop 0
	v_addc_co_u32_e32 v39, vcc, 0, v55, vcc
	v_add_co_u32_e32 v42, vcc, s44, v54
	global_load_dwordx4 v[34:37], v[34:35], off
	s_nop 0
	global_load_dwordx4 v[38:41], v[38:39], off
	v_addc_co_u32_e32 v43, vcc, 0, v55, vcc
	v_add_co_u32_e32 v46, vcc, s45, v54
	s_and_b32 s12, s12, 0xffffff00
	s_nop 0
	v_addc_co_u32_e32 v47, vcc, 0, v55, vcc
	global_load_dwordx4 v[42:45], v[42:43], off
	s_nop 0
	global_load_dwordx4 v[46:49], v[46:47], off
	v_add_co_u32_e32 v50, vcc, s46, v54
	s_nop 1
	v_addc_co_u32_e32 v51, vcc, 0, v55, vcc
	global_load_dwordx4 v[50:53], v[50:51], off
	v_add_co_u32_e32 v54, vcc, s47, v54
	s_nop 1
	v_addc_co_u32_e32 v55, vcc, 0, v55, vcc
	global_load_dwordx4 v[54:57], v[54:55], off
	s_waitcnt vmcnt(7)
	ds_write2_b32 v11, v26, v27 offset1:1
	ds_write2_b32 v11, v28, v29 offset0:2 offset1:3
	s_waitcnt vmcnt(6)
	ds_write2_b32 v12, v30, v31 offset1:1
	ds_write2_b32 v13, v32, v33 offset1:1
	s_waitcnt vmcnt(5)
	ds_write2_b32 v14, v34, v35 offset1:1
	ds_write2_b32 v15, v36, v37 offset1:1
	s_waitcnt vmcnt(4)
	ds_write2_b32 v16, v38, v39 offset1:1
	ds_write2_b32 v17, v40, v41 offset1:1
	s_waitcnt vmcnt(3)
	ds_write2_b32 v18, v42, v43 offset1:1
	ds_write2_b32 v19, v44, v45 offset1:1
	s_waitcnt vmcnt(2)
	ds_write2_b32 v20, v46, v47 offset1:1
	ds_write2_b32 v21, v48, v49 offset1:1
	s_waitcnt vmcnt(1)
	ds_write2_b32 v22, v50, v51 offset1:1
	ds_write2_b32 v23, v52, v53 offset1:1
	s_waitcnt vmcnt(0)
	ds_write2_b32 v24, v54, v55 offset1:1
	ds_write2_b32 v25, v56, v57 offset1:1
	v_lshl_add_u64 v[30:31], s[14:15], 1, v[4:5]
	s_and_b32 s14, s18, 0x60
	s_or_b32 s12, s12, s14
	s_waitcnt lgkmcnt(0)
	v_or_b32_e32 v34, s12, v6
	ds_read2_b32 v[100:101], v10 offset1:33
	ds_read2_b32 v[102:103], v10 offset0:66 offset1:99
	ds_read2_b32 v[104:105], v10 offset0:132 offset1:165
	ds_read2_b32 v[106:107], v10 offset0:198 offset1:231
	ds_read2_b32 v[108:109], v10 offset0:8 offset1:41
	ds_read2_b32 v[110:111], v10 offset0:74 offset1:107
	ds_read2_b32 v[112:113], v10 offset0:140 offset1:173
	ds_read2_b32 v[114:115], v10 offset0:206 offset1:239
	ds_read2_b32 v[116:117], v10 offset0:16 offset1:49
	ds_read2_b32 v[118:119], v10 offset0:82 offset1:115
	ds_read2_b32 v[120:121], v10 offset0:148 offset1:181
	ds_read2_b32 v[122:123], v10 offset0:214 offset1:247
	ds_read2_b32 v[124:125], v10 offset0:24 offset1:57
	ds_read2_b32 v[126:127], v10 offset0:90 offset1:123
	ds_read2_b32 v[128:129], v10 offset0:156 offset1:189
	ds_read2_b32 v[130:131], v10 offset0:222 offset1:255
	v_ashrrev_i32_e32 v35, 31, v34
	s_waitcnt lgkmcnt(15)
	v_cvt_pk_bf16_f32 v26, v100, v101
	v_lshlrev_b64 v[34:35], 12, v[34:35]
	s_waitcnt lgkmcnt(14)
	v_cvt_pk_bf16_f32 v27, v102, v103
	v_lshl_add_u64 v[34:35], v[30:31], 0, v[34:35]
	s_waitcnt lgkmcnt(13)
	v_cvt_pk_bf16_f32 v28, v104, v105
	s_waitcnt lgkmcnt(12)
	v_cvt_pk_bf16_f32 v29, v106, v107
	global_store_dwordx4 v[34:35], v[26:29], off
	v_or_b32_e32 v34, s12, v7
	v_ashrrev_i32_e32 v35, 31, v34
	s_waitcnt lgkmcnt(11)
	v_cvt_pk_bf16_f32 v26, v108, v109
	v_lshlrev_b64 v[34:35], 12, v[34:35]
	s_waitcnt lgkmcnt(10)
	v_cvt_pk_bf16_f32 v27, v110, v111
	v_lshl_add_u64 v[34:35], v[30:31], 0, v[34:35]
	s_waitcnt lgkmcnt(9)
	v_cvt_pk_bf16_f32 v28, v112, v113
	s_waitcnt lgkmcnt(8)
	v_cvt_pk_bf16_f32 v29, v114, v115
	global_store_dwordx4 v[34:35], v[26:29], off
	v_or_b32_e32 v34, s12, v8
	v_ashrrev_i32_e32 v35, 31, v34
	s_waitcnt lgkmcnt(7)
	v_cvt_pk_bf16_f32 v26, v116, v117
	v_lshlrev_b64 v[34:35], 12, v[34:35]
	s_waitcnt lgkmcnt(6)
	v_cvt_pk_bf16_f32 v27, v118, v119
	v_lshl_add_u64 v[34:35], v[30:31], 0, v[34:35]
	s_waitcnt lgkmcnt(5)
	v_cvt_pk_bf16_f32 v28, v120, v121
	s_waitcnt lgkmcnt(4)
	v_cvt_pk_bf16_f32 v29, v122, v123
	global_store_dwordx4 v[34:35], v[26:29], off
	v_or_b32_e32 v34, s12, v9
	v_ashrrev_i32_e32 v35, 31, v34
	s_waitcnt lgkmcnt(3)
	v_cvt_pk_bf16_f32 v26, v124, v125
	v_lshlrev_b64 v[34:35], 12, v[34:35]
	s_waitcnt lgkmcnt(2)
	v_cvt_pk_bf16_f32 v27, v126, v127
	v_lshl_add_u64 v[30:31], v[30:31], 0, v[34:35]
	s_waitcnt lgkmcnt(1)
	v_cvt_pk_bf16_f32 v28, v128, v129
	s_waitcnt lgkmcnt(0)
	v_cvt_pk_bf16_f32 v29, v130, v131
	global_store_dwordx4 v[30:31], v[26:29], off
	s_waitcnt lgkmcnt(0)
	s_branch .LBB0_1169

; __device__ __forceinline__ unsigned cvt_pk_bf16(float lo, float hi) { unsigned r; asm volatile("v_cvt_pk_bf16_f32 %0, %1, %2" : "=v"(r) : "v"(lo), "v"(hi)); return r; }
; #define LAS __attribute__((address_space(3)))
; __device__ __forceinline__ void transpose_item(const float* W, int K, int N, bf16_t* WT, const float* kscale, int kind, LAS float* scr, int item, int lane) {
;     const int nblk = N / 32, kb = item / nblk, nb = item % nblk, k0 = 64 * kb, n0 = 32 * nb;
;     {
;         const float* src = W + (size_t)(k0 + (lane >> 3)) * N + n0 + (lane & 7) * 4;
;         f32x4 t[8];
; #pragma unroll
;         for (int i = 0; i < 8; ++i) t[i] = *(const f32x4*)(src + (size_t)(8 * i) * N);
; #pragma unroll
;         for (int i = 0; i < 8; ++i) {
;             const int kk = 8 * i + (lane >> 3);
;             f32x4 v = t[i]; if (kscale) v = v * kscale[k0 + kk];
;             LAS float* d = scr + kk * 33 + (lane & 7) * 4;
;             d[0] = v[0]; d[1] = v[1]; d[2] = v[2]; d[3] = v[3];
;         }
;     }
;     asm volatile("s_waitcnt lgkmcnt(0)" ::: "memory");
;     const int c = lane & 7;
; #pragma unroll
;     for (int j = 0; j < 4; ++j) {
;         const int n = (lane >> 3) + 8 * j; const LAS float* s = scr + (8 * c) * 33 + n;
;         int drow; float sc; map_col(kind, n0 + n, drow, sc);
;         u32x4 ov; ov.x = cvt_pk_bf16(s[0 * 33] * sc, s[1 * 33] * sc); ov.y = cvt_pk_bf16(s[2 * 33] * sc, s[3 * 33] * sc); ov.z = cvt_pk_bf16(s[4 * 33] * sc, s[5 * 33] * sc); ov.w = cvt_pk_bf16(s[6 * 33] * sc, s[7 * 33] * sc);
;         *(u32x4*)(WT + (size_t)drow * K + k0 + 8 * c) = ov;
;     }
;     asm volatile("s_waitcnt lgkmcnt(0)" ::: "memory");
; }
; template <bool DRAIN>
; __device__ __forceinline__ void bg_convert(const float* wg1, const float* wu1, const float* wd1, unsigned char* wsw, unsigned* ctl, int done_word, int G, LAS float* scr, int lane) {
;     ...
;         for (int i = i0; i < i0 + 4; ++i) {
;             const int m = i / BG_ITEMS_PER, it = i - m * BG_ITEMS_PER;
;             if (m == 0) transpose_item(wg1, DM, FFN, (bf16_t*)(wsw + W1_GU), nullptr, MAP_GATE, scr, it, lane);
;             else if (m == 1) transpose_item(wu1, DM, FFN, (bf16_t*)(wsw + W1_GU), nullptr, MAP_UP, scr, it, lane);
;             else transpose_item(wd1, FFN, DM, (bf16_t*)(wsw + W1_DN), nullptr, MAP_ID, scr, it, lane);
.LBB0_1334:
	s_add_i32 s12, s20, 0xffffea00
	s_cmpk_gt_u32 s12, 0x15ff
	s_cbranch_scc0 .LBB0_1336
	s_sext_i32_i16 s12, s22
	s_bfe_u32 s12, s12, 0x60019
	s_add_i32 s12, s22, s12
	s_sext_i32_i16 s18, s12
	s_and_b32 s12, s12, 0xffc0
	s_and_b32 s54, s18, 0xffffffc0
	s_sub_i32 s12, s22, s12
	v_or_b32_e32 v30, s54, v6
	s_sext_i32_i16 s12, s12
	v_ashrrev_i32_e32 v31, 31, v30
	s_lshl_b32 s18, s12, 5
	v_lshlrev_b64 v[30:31], 13, v[30:31]
	v_lshl_add_u64 v[30:31], s[16:17], 0, v[30:31]
	s_ashr_i32 s19, s18, 31
	v_lshl_add_u64 v[30:31], s[18:19], 2, v[30:31]
	v_lshl_add_u64 v[58:59], v[30:31], 0, v[0:1]
	v_add_co_u32_e32 v34, vcc, s24, v58
	s_ashr_i32 s55, s54, 31
	s_nop 0
	v_addc_co_u32_e32 v35, vcc, 0, v59, vcc
	v_add_co_u32_e32 v38, vcc, s25, v58
	global_load_dwordx4 v[30:33], v[58:59], off
	s_nop 0
	global_load_dwordx4 v[34:37], v[34:35], off
	v_addc_co_u32_e32 v39, vcc, 0, v59, vcc
	v_add_co_u32_e32 v42, vcc, s26, v58
	v_or_b32_e32 v29, s18, v6
	s_nop 0
	v_addc_co_u32_e32 v43, vcc, 0, v59, vcc
	v_add_co_u32_e32 v46, vcc, s27, v58
	global_load_dwordx4 v[38:41], v[38:39], off
	s_nop 0
	global_load_dwordx4 v[42:45], v[42:43], off
	v_addc_co_u32_e32 v47, vcc, 0, v59, vcc
	v_add_co_u32_e32 v50, vcc, s38, v58
	s_nop 1
	v_addc_co_u32_e32 v51, vcc, 0, v59, vcc
	global_load_dwordx4 v[46:49], v[46:47], off
	s_nop 0
	global_load_dwordx4 v[50:53], v[50:51], off
	v_add_co_u32_e32 v54, vcc, s39, v58
	s_nop 1
	v_addc_co_u32_e32 v55, vcc, 0, v59, vcc
	global_load_dwordx4 v[54:57], v[54:55], off
	v_add_co_u32_e32 v58, vcc, s40, v58
	s_nop 1
	v_addc_co_u32_e32 v59, vcc, 0, v59, vcc
	global_load_dwordx4 v[58:61], v[58:59], off
	s_waitcnt vmcnt(7)
	ds_write2_b32 v11, v30, v31 offset1:1
	ds_write2_b32 v11, v32, v33 offset0:2 offset1:3
	s_waitcnt vmcnt(6)
	ds_write2_b32 v12, v34, v35 offset1:1
	ds_write2_b32 v13, v36, v37 offset1:1
	s_waitcnt vmcnt(5)
	ds_write2_b32 v14, v38, v39 offset1:1
	ds_write2_b32 v15, v40, v41 offset1:1
	s_waitcnt vmcnt(4)
	ds_write2_b32 v16, v42, v43 offset1:1
	ds_write2_b32 v17, v44, v45 offset1:1
	s_waitcnt vmcnt(3)
	ds_write2_b32 v18, v46, v47 offset1:1
	ds_write2_b32 v19, v48, v49 offset1:1
	s_waitcnt vmcnt(2)
	ds_write2_b32 v20, v50, v51 offset1:1
	ds_write2_b32 v21, v52, v53 offset1:1
	s_waitcnt vmcnt(1)
	ds_write2_b32 v22, v54, v55 offset1:1
	ds_write2_b32 v23, v56, v57 offset1:1
	s_waitcnt vmcnt(0)
	ds_write2_b32 v24, v58, v59 offset1:1
	ds_write2_b32 v25, v60, v61 offset1:1
	s_waitcnt lgkmcnt(0)
	ds_read2_b32 v[100:101], v10 offset1:33
	ds_read2_b32 v[102:103], v10 offset0:66 offset1:99
	ds_read2_b32 v[104:105], v10 offset0:132 offset1:165
	ds_read2_b32 v[106:107], v10 offset0:198 offset1:231
	ds_read2_b32 v[108:109], v10 offset0:8 offset1:41
	ds_read2_b32 v[110:111], v10 offset0:74 offset1:107
	ds_read2_b32 v[112:113], v10 offset0:140 offset1:173
	ds_read2_b32 v[114:115], v10 offset0:206 offset1:239
	ds_read2_b32 v[116:117], v10 offset0:16 offset1:49
	ds_read2_b32 v[118:119], v10 offset0:82 offset1:115
	ds_read2_b32 v[120:121], v10 offset0:148 offset1:181
	ds_read2_b32 v[122:123], v10 offset0:214 offset1:247
	ds_read2_b32 v[124:125], v10 offset0:24 offset1:57
	ds_read2_b32 v[126:127], v10 offset0:90 offset1:123
	ds_read2_b32 v[128:129], v10 offset0:156 offset1:189
	ds_read2_b32 v[130:131], v10 offset0:222 offset1:255
	s_waitcnt lgkmcnt(15)
	v_cvt_pk_bf16_f32 v30, v100, v101
	s_waitcnt lgkmcnt(14)
	v_cvt_pk_bf16_f32 v31, v102, v103
	v_lshl_add_u64 v[36:37], s[54:55], 1, v[2:3]
	s_waitcnt lgkmcnt(13)
	v_cvt_pk_bf16_f32 v32, v104, v105
	s_waitcnt lgkmcnt(12)
	v_cvt_pk_bf16_f32 v33, v106, v107
	v_mad_i64_i32 v[38:39], s[54:55], v29, s41, v[36:37]
	global_store_dwordx4 v[38:39], v[30:33], off
	v_or_b32_e32 v29, s18, v7
	v_mad_i64_i32 v[38:39], s[54:55], v29, s41, v[36:37]
	s_waitcnt lgkmcnt(11)
	v_cvt_pk_bf16_f32 v30, v108, v109
	s_waitcnt lgkmcnt(10)
	v_cvt_pk_bf16_f32 v31, v110, v111
	s_waitcnt lgkmcnt(9)
	v_cvt_pk_bf16_f32 v32, v112, v113
	s_waitcnt lgkmcnt(8)
	v_cvt_pk_bf16_f32 v33, v114, v115
	global_store_dwordx4 v[38:39], v[30:33], off
	v_or_b32_e32 v29, s18, v8
	v_mad_i64_i32 v[38:39], s[54:55], v29, s41, v[36:37]
	s_waitcnt lgkmcnt(7)
	v_cvt_pk_bf16_f32 v30, v116, v117
	s_waitcnt lgkmcnt(6)
	v_cvt_pk_bf16_f32 v31, v118, v119
	s_waitcnt lgkmcnt(5)
	v_cvt_pk_bf16_f32 v32, v120, v121
	s_waitcnt lgkmcnt(4)
	v_cvt_pk_bf16_f32 v33, v122, v123
	global_store_dwordx4 v[38:39], v[30:33], off
	v_add_u32_e32 v29, s18, v9
	s_waitcnt lgkmcnt(3)
	v_cvt_pk_bf16_f32 v30, v124, v125
	s_waitcnt lgkmcnt(2)
	v_cvt_pk_bf16_f32 v31, v126, v127
	s_waitcnt lgkmcnt(1)
	v_cvt_pk_bf16_f32 v32, v128, v129
	s_waitcnt lgkmcnt(0)
	v_cvt_pk_bf16_f32 v33, v130, v131
	v_mad_i64_i32 v[34:35], s[18:19], v29, s41, v[36:37]
	global_store_dwordx4 v[34:35], v[30:33], off
	s_waitcnt lgkmcnt(0)
	s_mov_b64 s[18:19], 0
; __device__ __forceinline__ unsigned cvt_pk_bf16(float lo, float hi) { unsigned r; asm volatile("v_cvt_pk_bf16_f32 %0, %1, %2" : "=v"(r) : "v"(lo), "v"(hi)); return r; }
; #define LAS __attribute__((address_space(3)))
; __device__ __forceinline__ void transpose_item(const float* W, int K, int N, bf16_t* WT, const float* kscale, int kind, LAS float* scr, int item, int lane) {
;     const int nblk = N / 32, kb = item / nblk, nb = item % nblk, k0 = 64 * kb, n0 = 32 * nb;
;     {
;         const float* src = W + (size_t)(k0 + (lane >> 3)) * N + n0 + (lane & 7) * 4;
;         f32x4 t[8];
; #pragma unroll
;         for (int i = 0; i < 8; ++i) t[i] = *(const f32x4*)(src + (size_t)(8 * i) * N);
; #pragma unroll
;         for (int i = 0; i < 8; ++i) {
;             const int kk = 8 * i + (lane >> 3);
;             f32x4 v = t[i]; if (kscale) v = v * kscale[k0 + kk];
;             LAS float* d = scr + kk * 33 + (lane & 7) * 4;
;             d[0] = v[0]; d[1] = v[1]; d[2] = v[2]; d[3] = v[3];
;         }
;     }
;     asm volatile("s_waitcnt lgkmcnt(0)" ::: "memory");
;     const int c = lane & 7;
; #pragma unroll
;     for (int j = 0; j < 4; ++j) {
;         const int n = (lane >> 3) + 8 * j; const LAS float* s = scr + (8 * c) * 33 + n;
;         int drow; float sc; map_col(kind, n0 + n, drow, sc);
;         u32x4 ov; ov.x = cvt_pk_bf16(s[0 * 33] * sc, s[1 * 33] * sc); ov.y = cvt_pk_bf16(s[2 * 33] * sc, s[3 * 33] * sc); ov.z = cvt_pk_bf16(s[4 * 33] * sc, s[5 * 33] * sc); ov.w = cvt_pk_bf16(s[6 * 33] * sc, s[7 * 33] * sc);
;         *(u32x4*)(WT + (size_t)drow * K + k0 + 8 * c) = ov;
;     }
;     asm volatile("s_waitcnt lgkmcnt(0)" ::: "memory");
; }
; template <bool DRAIN>
; __device__ __forceinline__ void bg_convert(const float* wg1, const float* wu1, const float* wd1, unsigned char* wsw, unsigned* ctl, int done_word, int G, LAS float* scr, int lane) {
;     ...
;         for (int i = i0; i < i0 + 4; ++i) {
;             const int m = i / BG_ITEMS_PER, it = i - m * BG_ITEMS_PER;
;             if (m == 0) transpose_item(wg1, DM, FFN, (bf16_t*)(wsw + W1_GU), nullptr, MAP_GATE, scr, it, lane);
;             else if (m == 1) transpose_item(wu1, DM, FFN, (bf16_t*)(wsw + W1_GU), nullptr, MAP_UP, scr, it, lane);
;             else transpose_item(wd1, FFN, DM, (bf16_t*)(wsw + W1_DN), nullptr, MAP_ID, scr, it, lane);
.LBB0_1336:
	s_andn2_b64 vcc, exec, s[18:19]
	s_cbranch_vccnz .LBB0_1338
	s_and_b32 s12, 0xffff, s22
	s_mul_i32 s12, s12, 0xba2f
	s_lshr_b32 s19, s12, 23
	s_mul_i32 s12, s19, 0xb0
	s_sub_i32 s12, s22, s12
	s_lshl_b32 s12, s12, 5
	s_and_b32 s18, s12, 0xffe0
	v_lshl_or_b32 v29, s19, 6, v6
	v_mov_b64_e32 v[30:31], s[8:9]
	v_mad_u64_u32 v[30:31], s[54:55], v29, s42, v[30:31]
	s_lshl_b32 s12, s18, 2
	v_lshl_add_u64 v[30:31], v[30:31], 0, s[12:13]
	v_lshl_add_u64 v[58:59], v[30:31], 0, v[0:1]
	v_add_co_u32_e32 v34, vcc, s43, v58
	v_mov_b32_e32 v29, s18
	s_nop 0
	v_addc_co_u32_e32 v35, vcc, 0, v59, vcc
	v_add_co_u32_e32 v38, vcc, s44, v58
	global_load_dwordx4 v[30:33], v[58:59], off
	s_nop 0
	global_load_dwordx4 v[34:37], v[34:35], off
	v_addc_co_u32_e32 v39, vcc, 0, v59, vcc
	v_add_co_u32_e32 v42, vcc, s45, v58
	s_lshl_b32 s23, s18, 1
	s_nop 0
	v_addc_co_u32_e32 v43, vcc, 0, v59, vcc
	v_add_co_u32_e32 v46, vcc, s46, v58
	global_load_dwordx4 v[38:41], v[38:39], off
	s_nop 0
	global_load_dwordx4 v[42:45], v[42:43], off
	v_addc_co_u32_e32 v47, vcc, 0, v59, vcc
	v_add_co_u32_e32 v50, vcc, s47, v58
	s_lshl_b32 s12, s19, 7
	s_nop 0
	v_addc_co_u32_e32 v51, vcc, 0, v59, vcc
	global_load_dwordx4 v[46:49], v[46:47], off
	s_nop 0
	global_load_dwordx4 v[50:53], v[50:51], off
	v_add_co_u32_e32 v54, vcc, s48, v58
	s_and_b32 s19, s23, 0xff00
	s_nop 0
	v_addc_co_u32_e32 v55, vcc, 0, v59, vcc
	global_load_dwordx4 v[54:57], v[54:55], off
	v_add_co_u32_e32 v58, vcc, s49, v58
	s_nop 1
	v_addc_co_u32_e32 v59, vcc, 0, v59, vcc
	global_load_dwordx4 v[58:61], v[58:59], off
	s_waitcnt vmcnt(7)
	ds_write2_b32 v11, v30, v31 offset1:1
	ds_write2_b32 v11, v32, v33 offset0:2 offset1:3
	s_waitcnt vmcnt(6)
	ds_write2_b32 v12, v34, v35 offset1:1
	ds_write2_b32 v13, v36, v37 offset1:1
	s_waitcnt vmcnt(5)
	ds_write2_b32 v14, v38, v39 offset1:1
	ds_write2_b32 v15, v40, v41 offset1:1
	s_waitcnt vmcnt(4)
	ds_write2_b32 v16, v42, v43 offset1:1
	ds_write2_b32 v17, v44, v45 offset1:1
	s_waitcnt vmcnt(3)
	ds_write2_b32 v18, v46, v47 offset1:1
	ds_write2_b32 v19, v48, v49 offset1:1
	s_waitcnt vmcnt(2)
	ds_write2_b32 v20, v50, v51 offset1:1
	ds_write2_b32 v21, v52, v53 offset1:1
	s_waitcnt vmcnt(1)
	ds_write2_b32 v22, v54, v55 offset1:1
	ds_write2_b32 v23, v56, v57 offset1:1
	s_waitcnt vmcnt(0)
	ds_write2_b32 v24, v58, v59 offset1:1
	ds_write2_b32 v25, v60, v61 offset1:1
	s_waitcnt lgkmcnt(0)
	ds_read2_b32 v[100:101], v10 offset1:33
	ds_read2_b32 v[102:103], v10 offset0:66 offset1:99
	ds_read2_b32 v[104:105], v10 offset0:132 offset1:165
	ds_read2_b32 v[106:107], v10 offset0:198 offset1:231
	ds_read2_b32 v[108:109], v10 offset0:8 offset1:41
	ds_read2_b32 v[110:111], v10 offset0:74 offset1:107
	ds_read2_b32 v[112:113], v10 offset0:140 offset1:173
	ds_read2_b32 v[114:115], v10 offset0:206 offset1:239
	ds_read2_b32 v[116:117], v10 offset0:16 offset1:49
	ds_read2_b32 v[118:119], v10 offset0:82 offset1:115
	ds_read2_b32 v[120:121], v10 offset0:148 offset1:181
	ds_read2_b32 v[122:123], v10 offset0:214 offset1:247
	ds_read2_b32 v[124:125], v10 offset0:24 offset1:57
	ds_read2_b32 v[126:127], v10 offset0:90 offset1:123
	ds_read2_b32 v[128:129], v10 offset0:156 offset1:189
	ds_read2_b32 v[130:131], v10 offset0:222 offset1:255
	s_waitcnt lgkmcnt(15)
	v_cvt_pk_bf16_f32 v30, v100, v101
	v_bitop3_b32 v34, v6, s50, v29 bitop3:0xc8
	s_waitcnt lgkmcnt(14)
	v_cvt_pk_bf16_f32 v31, v102, v103
	v_or_b32_e32 v34, s19, v34
	v_mov_b32_e32 v35, v1
	s_waitcnt lgkmcnt(13)
	v_cvt_pk_bf16_f32 v32, v104, v105
	v_lshl_add_u64 v[38:39], v[4:5], 0, s[12:13]
	v_lshl_or_b32 v34, v34, 12, v26
	s_waitcnt lgkmcnt(12)
	v_cvt_pk_bf16_f32 v33, v106, v107
	v_lshl_add_u64 v[34:35], v[38:39], 0, v[34:35]
	global_store_dwordx4 v[34:35], v[30:33], off
	s_nop 0
	s_waitcnt lgkmcnt(11)
	v_cvt_pk_bf16_f32 v30, v108, v109
	v_bitop3_b32 v36, v7, s51, v29 bitop3:0xc8
	v_or_b32_e32 v36, s19, v36
	s_waitcnt lgkmcnt(10)
	v_cvt_pk_bf16_f32 v31, v110, v111
	v_mov_b32_e32 v37, v1
	v_lshl_or_b32 v36, v36, 12, v26
	s_waitcnt lgkmcnt(9)
	v_cvt_pk_bf16_f32 v32, v112, v113
	s_waitcnt lgkmcnt(8)
	v_cvt_pk_bf16_f32 v33, v114, v115
	v_lshl_add_u64 v[36:37], v[38:39], 0, v[36:37]
	v_bitop3_b32 v29, v8, s51, v29 bitop3:0xc8
	global_store_dwordx4 v[36:37], v[30:33], off
	v_or_b32_e32 v29, s19, v29
	v_mov_b32_e32 v37, v1
	s_waitcnt lgkmcnt(7)
	v_cvt_pk_bf16_f32 v30, v116, v117
	s_waitcnt lgkmcnt(6)
	v_cvt_pk_bf16_f32 v31, v118, v119
	v_lshl_or_b32 v36, v29, 12, v26
	s_waitcnt lgkmcnt(5)
	v_cvt_pk_bf16_f32 v32, v120, v121
	s_waitcnt lgkmcnt(4)
	v_cvt_pk_bf16_f32 v33, v122, v123
	v_lshl_add_u64 v[36:37], v[38:39], 0, v[36:37]
	global_store_dwordx4 v[36:37], v[30:33], off
	v_add_u32_e32 v29, s18, v9
	s_waitcnt lgkmcnt(3)
	v_cvt_pk_bf16_f32 v30, v124, v125
	s_waitcnt lgkmcnt(2)
	v_cvt_pk_bf16_f32 v31, v126, v127
	s_waitcnt lgkmcnt(1)
	v_cvt_pk_bf16_f32 v32, v128, v129
	v_lshlrev_b32_e32 v33, 1, v29
	v_and_b32_e32 v33, 0x1ff00, v33
	v_and_or_b32 v29, v29, s51, v33
	v_mov_b32_e32 v35, v1
	v_lshl_or_b32 v34, v29, 12, v26
	v_lshl_add_u64 v[34:35], v[38:39], 0, v[34:35]
	s_waitcnt lgkmcnt(0)
	v_cvt_pk_bf16_f32 v33, v130, v131
	global_store_dwordx4 v[34:35], v[30:33], off
	s_waitcnt lgkmcnt(0)

; __device__ __forceinline__ unsigned cvt_pk_bf16(float lo, float hi) { unsigned r; asm volatile("v_cvt_pk_bf16_f32 %0, %1, %2" : "=v"(r) : "v"(lo), "v"(hi)); return r; }
; #define LAS __attribute__((address_space(3)))
; __device__ __forceinline__ void transpose_item(const float* W, int K, int N, bf16_t* WT, const float* kscale, int kind, LAS float* scr, int item, int lane) {
;     const int nblk = N / 32, kb = item / nblk, nb = item % nblk, k0 = 64 * kb, n0 = 32 * nb;
;     {
;         const float* src = W + (size_t)(k0 + (lane >> 3)) * N + n0 + (lane & 7) * 4;
;         f32x4 t[8];
; #pragma unroll
;         for (int i = 0; i < 8; ++i) t[i] = *(const f32x4*)(src + (size_t)(8 * i) * N);
; #pragma unroll
;         for (int i = 0; i < 8; ++i) {
;             const int kk = 8 * i + (lane >> 3);
;             f32x4 v = t[i]; if (kscale) v = v * kscale[k0 + kk];
;             LAS float* d = scr + kk * 33 + (lane & 7) * 4;
;             d[0] = v[0]; d[1] = v[1]; d[2] = v[2]; d[3] = v[3];
;         }
;     }
;     asm volatile("s_waitcnt lgkmcnt(0)" ::: "memory");
;     const int c = lane & 7;
; #pragma unroll
;     for (int j = 0; j < 4; ++j) {
;         const int n = (lane >> 3) + 8 * j; const LAS float* s = scr + (8 * c) * 33 + n;
;         int drow; float sc; map_col(kind, n0 + n, drow, sc);
;         u32x4 ov; ov.x = cvt_pk_bf16(s[0 * 33] * sc, s[1 * 33] * sc); ov.y = cvt_pk_bf16(s[2 * 33] * sc, s[3 * 33] * sc); ov.z = cvt_pk_bf16(s[4 * 33] * sc, s[5 * 33] * sc); ov.w = cvt_pk_bf16(s[6 * 33] * sc, s[7 * 33] * sc);
;         *(u32x4*)(WT + (size_t)drow * K + k0 + 8 * c) = ov;
;     }
;     asm volatile("s_waitcnt lgkmcnt(0)" ::: "memory");
; }
; template <bool DRAIN>
; __device__ __forceinline__ void bg_convert(const float* wg1, const float* wu1, const float* wd1, unsigned char* wsw, unsigned* ctl, int done_word, int G, LAS float* scr, int lane) {
;     ...
;         for (int i = i0; i < i0 + 4; ++i) {
;             const int m = i / BG_ITEMS_PER, it = i - m * BG_ITEMS_PER;
;             if (m == 0) transpose_item(wg1, DM, FFN, (bf16_t*)(wsw + W1_GU), nullptr, MAP_GATE, scr, it, lane);
;             else if (m == 1) transpose_item(wu1, DM, FFN, (bf16_t*)(wsw + W1_GU), nullptr, MAP_UP, scr, it, lane);
;             else transpose_item(wd1, FFN, DM, (bf16_t*)(wsw + W1_DN), nullptr, MAP_ID, scr, it, lane);
.LBB0_1339:
	s_sext_i32_i16 s12, s22
	s_mulk_i32 s12, 0xba3
	s_lshr_b32 s18, s12, 31
	s_ashr_i32 s12, s12, 19
	s_add_i32 s12, s12, s18
	s_mul_i32 s18, s12, 0xb0
	s_sub_i32 s18, s22, s18
	s_sext_i32_i16 s53, s18
	s_lshl_b32 s22, s12, 6
	s_lshl_b32 s18, s53, 5
	v_or_b32_e32 v29, s22, v6
	v_mov_b64_e32 v[30:31], s[6:7]
	v_mad_i64_i32 v[30:31], s[54:55], v29, s42, v[30:31]
	s_ashr_i32 s19, s18, 31
	v_lshl_add_u64 v[30:31], s[18:19], 2, v[30:31]
	v_lshl_add_u64 v[58:59], v[30:31], 0, v[0:1]
	v_add_co_u32_e32 v34, vcc, s43, v58
	s_lshl_b32 s12, s53, 6
	s_nop 0
	v_addc_co_u32_e32 v35, vcc, 0, v59, vcc
	v_add_co_u32_e32 v38, vcc, s44, v58
	global_load_dwordx4 v[30:33], v[58:59], off
	s_nop 0
	global_load_dwordx4 v[34:37], v[34:35], off
	v_addc_co_u32_e32 v39, vcc, 0, v59, vcc
	v_add_co_u32_e32 v42, vcc, s45, v58
	v_bitop3_b32 v29, s18, v27, v6 bitop3:0xc8
	s_nop 0
	v_addc_co_u32_e32 v43, vcc, 0, v59, vcc
	v_add_co_u32_e32 v46, vcc, s46, v58
	global_load_dwordx4 v[38:41], v[38:39], off
	s_nop 0
	global_load_dwordx4 v[42:45], v[42:43], off
	v_addc_co_u32_e32 v47, vcc, 0, v59, vcc
	v_add_co_u32_e32 v50, vcc, s47, v58
	s_and_b32 s12, s12, 0xffffff00
	s_nop 0
	v_addc_co_u32_e32 v51, vcc, 0, v59, vcc
	global_load_dwordx4 v[46:49], v[46:47], off
	s_nop 0
	global_load_dwordx4 v[50:53], v[50:51], off
	v_add_co_u32_e32 v54, vcc, s48, v58
	s_ashr_i32 s23, s22, 31
	s_nop 0
	v_addc_co_u32_e32 v55, vcc, 0, v59, vcc
	global_load_dwordx4 v[54:57], v[54:55], off
	v_add_co_u32_e32 v58, vcc, s49, v58
	s_nop 1
	v_addc_co_u32_e32 v59, vcc, 0, v59, vcc
	global_load_dwordx4 v[58:61], v[58:59], off
	s_waitcnt vmcnt(7)
	ds_write2_b32 v11, v30, v31 offset1:1
	ds_write2_b32 v11, v32, v33 offset0:2 offset1:3
	s_waitcnt vmcnt(6)
	ds_write2_b32 v12, v34, v35 offset1:1
	ds_write2_b32 v13, v36, v37 offset1:1
	s_waitcnt vmcnt(5)
	ds_write2_b32 v14, v38, v39 offset1:1
	ds_write2_b32 v15, v40, v41 offset1:1
	s_waitcnt vmcnt(4)
	ds_write2_b32 v16, v42, v43 offset1:1
	ds_write2_b32 v17, v44, v45 offset1:1
	s_waitcnt vmcnt(3)
	ds_write2_b32 v18, v46, v47 offset1:1
	ds_write2_b32 v19, v48, v49 offset1:1
	s_waitcnt vmcnt(2)
	ds_write2_b32 v20, v50, v51 offset1:1
	ds_write2_b32 v21, v52, v53 offset1:1
	s_waitcnt vmcnt(1)
	ds_write2_b32 v22, v54, v55 offset1:1
	ds_write2_b32 v23, v56, v57 offset1:1
	s_waitcnt vmcnt(0)
	ds_write2_b32 v24, v58, v59 offset1:1
	ds_write2_b32 v25, v60, v61 offset1:1
	s_waitcnt lgkmcnt(0)
	v_or_b32_e32 v38, s12, v29
	ds_read2_b32 v[100:101], v10 offset1:33
	ds_read2_b32 v[102:103], v10 offset0:66 offset1:99
	ds_read2_b32 v[104:105], v10 offset0:132 offset1:165
	ds_read2_b32 v[106:107], v10 offset0:198 offset1:231
	ds_read2_b32 v[108:109], v10 offset0:8 offset1:41
	ds_read2_b32 v[110:111], v10 offset0:74 offset1:107
	ds_read2_b32 v[112:113], v10 offset0:140 offset1:173
	ds_read2_b32 v[114:115], v10 offset0:206 offset1:239
	ds_read2_b32 v[116:117], v10 offset0:16 offset1:49
	ds_read2_b32 v[118:119], v10 offset0:82 offset1:115
	ds_read2_b32 v[120:121], v10 offset0:148 offset1:181
	ds_read2_b32 v[122:123], v10 offset0:214 offset1:247
	ds_read2_b32 v[124:125], v10 offset0:24 offset1:57
	ds_read2_b32 v[126:127], v10 offset0:90 offset1:123
	ds_read2_b32 v[128:129], v10 offset0:156 offset1:189
	ds_read2_b32 v[130:131], v10 offset0:222 offset1:255
	v_ashrrev_i32_e32 v39, 31, v38
	s_waitcnt lgkmcnt(15)
	v_cvt_pk_bf16_f32 v30, v100, v101
	v_lshl_add_u64 v[34:35], s[22:23], 1, v[4:5]
	v_lshlrev_b64 v[38:39], 12, v[38:39]
	s_waitcnt lgkmcnt(14)
	v_cvt_pk_bf16_f32 v31, v102, v103
	v_lshl_add_u64 v[38:39], v[34:35], 0, v[38:39]
	v_bitop3_b32 v29, s18, v28, v7 bitop3:0xc8
	s_waitcnt lgkmcnt(13)
	v_cvt_pk_bf16_f32 v32, v104, v105
	s_waitcnt lgkmcnt(12)
	v_cvt_pk_bf16_f32 v33, v106, v107
	global_store_dwordx4 v[38:39], v[30:33], off
	v_or_b32_e32 v38, s12, v29
	v_ashrrev_i32_e32 v39, 31, v38
	s_waitcnt lgkmcnt(11)
	v_cvt_pk_bf16_f32 v30, v108, v109
	v_lshlrev_b64 v[38:39], 12, v[38:39]
	s_waitcnt lgkmcnt(10)
	v_cvt_pk_bf16_f32 v31, v110, v111
	v_lshl_add_u64 v[38:39], v[34:35], 0, v[38:39]
	v_bitop3_b32 v29, s18, v28, v8 bitop3:0xc8
	s_waitcnt lgkmcnt(9)
	v_cvt_pk_bf16_f32 v32, v112, v113
	s_waitcnt lgkmcnt(8)
	v_cvt_pk_bf16_f32 v33, v114, v115
	global_store_dwordx4 v[38:39], v[30:33], off
	v_or_b32_e32 v38, s12, v29
	v_ashrrev_i32_e32 v39, 31, v38
	s_waitcnt lgkmcnt(7)
	v_cvt_pk_bf16_f32 v30, v116, v117
	v_lshlrev_b64 v[38:39], 12, v[38:39]
	s_waitcnt lgkmcnt(6)
	v_cvt_pk_bf16_f32 v31, v118, v119
	v_lshl_add_u64 v[38:39], v[34:35], 0, v[38:39]
	v_add_u32_e32 v29, s18, v9
	s_waitcnt lgkmcnt(5)
	v_cvt_pk_bf16_f32 v32, v120, v121
	s_waitcnt lgkmcnt(4)
	v_cvt_pk_bf16_f32 v33, v122, v123
	global_store_dwordx4 v[38:39], v[30:33], off
	v_lshlrev_b32_e32 v38, 1, v29
	v_and_b32_e32 v29, 0x7f, v29
	v_and_or_b32 v38, v38, s52, v29
	v_ashrrev_i32_e32 v39, 31, v38
	s_waitcnt lgkmcnt(3)
	v_cvt_pk_bf16_f32 v30, v124, v125
	v_lshlrev_b64 v[38:39], 12, v[38:39]
	s_waitcnt lgkmcnt(2)
	v_cvt_pk_bf16_f32 v31, v126, v127
	v_lshl_add_u64 v[34:35], v[34:35], 0, v[38:39]
	s_waitcnt lgkmcnt(1)
	v_cvt_pk_bf16_f32 v32, v128, v129
	s_waitcnt lgkmcnt(0)
	v_cvt_pk_bf16_f32 v33, v130, v131
	global_store_dwordx4 v[34:35], v[30:33], off
	s_waitcnt lgkmcnt(0)
	s_branch .LBB0_1331
